# GEMM unit transitions: first K iteration peeled with SrcC=0 (no accumulator reset), shift/mask tile index division; s_nop padding keeps every K loop and later phase at its previous placement mod 64
# speedup vs baseline: 1.0057x; 1.0022x over previous
.LBB0_162:
	s_ashr_i32 s39, s38, 31
	s_lshl_b64 s[40:41], s[38:39], 19
	s_add_u32 s40, s74, s40
	s_addc_u32 s41, s75, s41
	s_and_b64 s[42:43], s[0:1], exec
	s_cselect_b32 s5, s41, s9
	s_cselect_b32 s7, s40, s8
	s_ashr_i32 s37, s36, 31
	s_lshl_b64 s[42:43], s[36:37], 19
	s_add_u32 s42, s16, s42
	s_addc_u32 s43, s17, s43
	s_and_b64 s[46:47], s[0:1], exec
	s_cselect_b32 s37, s43, s45
	s_cselect_b32 s39, s42, s44
	s_add_u32 s8, s8, 0x40080
	s_addc_u32 s9, s9, 0
	s_add_u32 s48, s44, 0x100
	s_addc_u32 s49, s45, 0
	s_mov_b32 s50, -2
	s_nop 0
	s_nop 0
	s_nop 0
	s_nop 0
	s_nop 0
	s_nop 0
	s_nop 0
	s_nop 0
	s_nop 0
	s_nop 0
	s_nop 0
	s_nop 0
	ds_read_b128 v[148:151], v155
	ds_read_b128 v[160:163], v155 offset:1024
	ds_read_b128 v[164:167], v155 offset:2048
	ds_read_b128 v[168:171], v155 offset:3072
	ds_read_b128 v[172:175], v156
	ds_read_b128 v[176:179], v156 offset:1024
	ds_read_b128 v[180:183], v156 offset:2048
	ds_read_b128 v[184:187], v156 offset:3072
	s_add_u32 s44, s8, 0xfffc0080
	s_addc_u32 s45, s9, -1
	s_cmp_eq_u32 s50, 12
	s_cselect_b32 s47, s5, s45
	s_cselect_b32 s46, s7, s44
	s_cselect_b32 s45, s37, s49
	s_cselect_b32 s44, s39, s48
	v_lshl_add_u64 v[222:223], s[8:9], 0, v[138:139]
	s_add_i32 m0, s20, 0xc000
	ds_read_b128 v[188:191], v157
	ds_read_b128 v[194:197], v157 offset:1024
	ds_read_b128 v[198:201], v157 offset:2048
	ds_read_b128 v[202:205], v157 offset:3072
	ds_read_b128 v[206:209], v157 offset:4096
	ds_read_b128 v[210:213], v157 offset:5120
	ds_read_b128 v[214:217], v157 offset:6144
	ds_read_b128 v[218:221], v157 offset:7168
	global_load_lds_dwordx4 v[222:223], off
	v_lshl_add_u64 v[222:223], s[8:9], 0, v[140:141]
	s_add_i32 m0, s20, 0xe000
	s_nop 0
	global_load_lds_dwordx4 v[222:223], off
	s_waitcnt vmcnt(8)
	s_waitcnt lgkmcnt(0)
	s_barrier
	s_waitcnt lgkmcnt(0)
	v_mfma_f32_16x16x32_bf16 v[124:127], v[148:151], v[188:191], 0
	v_mfma_f32_16x16x32_bf16 v[120:123], v[164:167], v[188:191], 0
	v_mfma_f32_16x16x32_bf16 v[108:111], v[148:151], v[198:201], 0
	v_mfma_f32_16x16x32_bf16 v[104:107], v[164:167], v[198:201], 0
	v_mfma_f32_16x16x32_bf16 v[96:99], v[148:151], v[206:209], 0
	v_mfma_f32_16x16x32_bf16 v[88:91], v[164:167], v[206:209], 0
	v_mfma_f32_16x16x32_bf16 v[84:87], v[148:151], v[214:217], 0
	v_mfma_f32_16x16x32_bf16 v[76:79], v[164:167], v[214:217], 0
	v_mfma_f32_16x16x32_bf16 v[124:127], v[160:163], v[194:197], v[124:127]
	v_mfma_f32_16x16x32_bf16 v[120:123], v[168:171], v[194:197], v[120:123]
	v_mfma_f32_16x16x32_bf16 v[108:111], v[160:163], v[202:205], v[108:111]
	v_mfma_f32_16x16x32_bf16 v[104:107], v[168:171], v[202:205], v[104:107]
	v_mfma_f32_16x16x32_bf16 v[96:99], v[160:163], v[210:213], v[96:99]
	v_mfma_f32_16x16x32_bf16 v[88:91], v[168:171], v[210:213], v[88:91]
	v_mfma_f32_16x16x32_bf16 v[84:87], v[160:163], v[218:221], v[84:87]
	v_mfma_f32_16x16x32_bf16 v[76:79], v[168:171], v[218:221], v[76:79]
	v_mfma_f32_16x16x32_bf16 v[116:119], v[172:175], v[188:191], 0
	v_mfma_f32_16x16x32_bf16 v[112:115], v[180:183], v[188:191], 0
	v_mfma_f32_16x16x32_bf16 v[100:103], v[172:175], v[198:201], 0
	v_mfma_f32_16x16x32_bf16 v[92:95], v[180:183], v[198:201], 0
	v_mfma_f32_16x16x32_bf16 v[80:83], v[172:175], v[206:209], 0
	v_mfma_f32_16x16x32_bf16 v[72:75], v[180:183], v[206:209], 0
	v_mfma_f32_16x16x32_bf16 v[68:71], v[172:175], v[214:217], 0
	v_mfma_f32_16x16x32_bf16 v[64:67], v[180:183], v[214:217], 0
	v_mfma_f32_16x16x32_bf16 v[116:119], v[176:179], v[194:197], v[116:119]
	v_mfma_f32_16x16x32_bf16 v[112:115], v[184:187], v[194:197], v[112:115]
	v_mfma_f32_16x16x32_bf16 v[100:103], v[176:179], v[202:205], v[100:103]
	v_mfma_f32_16x16x32_bf16 v[92:95], v[184:187], v[202:205], v[92:95]
	v_mfma_f32_16x16x32_bf16 v[80:83], v[176:179], v[210:213], v[80:83]
	v_mfma_f32_16x16x32_bf16 v[72:75], v[184:187], v[210:213], v[72:75]
	v_mfma_f32_16x16x32_bf16 v[68:71], v[176:179], v[218:221], v[68:71]
	v_mfma_f32_16x16x32_bf16 v[64:67], v[184:187], v[218:221], v[64:67]
	s_barrier
	s_add_i32 s51, s72, s15
	v_lshl_add_u64 v[222:223], s[44:45], 0, v[130:131]
	s_mov_b32 m0, s51
	ds_read_b128 v[188:191], v157 offset:16384
	ds_read_b128 v[194:197], v157 offset:17408
	ds_read_b128 v[198:201], v157 offset:18432
	ds_read_b128 v[202:205], v157 offset:19456
	ds_read_b128 v[206:209], v157 offset:20480
	ds_read_b128 v[210:213], v157 offset:21504
	ds_read_b128 v[214:217], v157 offset:22528
	ds_read_b128 v[218:221], v157 offset:23552
	global_load_lds_dwordx4 v[222:223], off
	s_add_i32 m0, s51, 0x2000
	s_add_u32 s64, s44, 0x40000
	v_lshl_add_u64 v[224:225], s[44:45], 0, v[134:135]
	s_addc_u32 s65, s45, 0
	s_add_i32 s51, s73, s15
	global_load_lds_dwordx4 v[224:225], off
	v_lshl_add_u64 v[226:227], s[64:65], 0, v[130:131]
	s_mov_b32 m0, s51
	v_lshl_add_u64 v[228:229], s[46:47], 0, v[132:133]
	global_load_lds_dwordx4 v[226:227], off
	v_lshl_add_u64 v[226:227], s[64:65], 0, v[134:135]
	s_add_i32 m0, s51, 0x2000
	s_nop 0
	global_load_lds_dwordx4 v[226:227], off
	v_lshl_add_u64 v[226:227], s[46:47], 0, v[128:129]
	s_mov_b32 m0, s20
	s_nop 0
	global_load_lds_dwordx4 v[226:227], off
	s_mov_b32 m0, s21
	s_nop 0
	global_load_lds_dwordx4 v[228:229], off
	s_waitcnt vmcnt(8)
	s_waitcnt lgkmcnt(0)
	s_barrier
	s_waitcnt lgkmcnt(0)
	v_mfma_f32_16x16x32_bf16 v[60:63], v[148:151], v[188:191], 0
	v_mfma_f32_16x16x32_bf16 v[56:59], v[164:167], v[188:191], 0
	v_mfma_f32_16x16x32_bf16 v[44:47], v[148:151], v[198:201], 0
	v_mfma_f32_16x16x32_bf16 v[40:43], v[164:167], v[198:201], 0
	v_mfma_f32_16x16x32_bf16 v[32:35], v[148:151], v[206:209], 0
	v_mfma_f32_16x16x32_bf16 v[24:27], v[164:167], v[206:209], 0
	v_mfma_f32_16x16x32_bf16 v[20:23], v[148:151], v[214:217], 0
	v_mfma_f32_16x16x32_bf16 v[12:15], v[164:167], v[214:217], 0
	v_mfma_f32_16x16x32_bf16 v[60:63], v[160:163], v[194:197], v[60:63]
	v_mfma_f32_16x16x32_bf16 v[56:59], v[168:171], v[194:197], v[56:59]
	v_mfma_f32_16x16x32_bf16 v[44:47], v[160:163], v[202:205], v[44:47]
	v_mfma_f32_16x16x32_bf16 v[40:43], v[168:171], v[202:205], v[40:43]
	v_mfma_f32_16x16x32_bf16 v[32:35], v[160:163], v[210:213], v[32:35]
	v_mfma_f32_16x16x32_bf16 v[24:27], v[168:171], v[210:213], v[24:27]
	v_mfma_f32_16x16x32_bf16 v[20:23], v[160:163], v[218:221], v[20:23]
	v_mfma_f32_16x16x32_bf16 v[12:15], v[168:171], v[218:221], v[12:15]
	v_mfma_f32_16x16x32_bf16 v[52:55], v[172:175], v[188:191], 0
	v_mfma_f32_16x16x32_bf16 v[48:51], v[180:183], v[188:191], 0
	v_mfma_f32_16x16x32_bf16 v[36:39], v[172:175], v[198:201], 0
	v_mfma_f32_16x16x32_bf16 v[28:31], v[180:183], v[198:201], 0
	v_mfma_f32_16x16x32_bf16 v[16:19], v[172:175], v[206:209], 0
	v_mfma_f32_16x16x32_bf16 v[8:11], v[180:183], v[206:209], 0
	v_mfma_f32_16x16x32_bf16 v[4:7], v[172:175], v[214:217], 0
	v_mfma_f32_16x16x32_bf16 v[0:3], v[180:183], v[214:217], 0
	v_mfma_f32_16x16x32_bf16 v[52:55], v[176:179], v[194:197], v[52:55]
	v_mfma_f32_16x16x32_bf16 v[48:51], v[184:187], v[194:197], v[48:51]
	v_mfma_f32_16x16x32_bf16 v[36:39], v[176:179], v[202:205], v[36:39]
	v_mfma_f32_16x16x32_bf16 v[28:31], v[184:187], v[202:205], v[28:31]
	v_mfma_f32_16x16x32_bf16 v[16:19], v[176:179], v[210:213], v[16:19]
	v_mfma_f32_16x16x32_bf16 v[8:11], v[184:187], v[210:213], v[8:11]
	v_mfma_f32_16x16x32_bf16 v[4:7], v[176:179], v[218:221], v[4:7]
	v_mfma_f32_16x16x32_bf16 v[0:3], v[184:187], v[218:221], v[0:3]
	s_barrier
	s_add_i32 s51, 0, 0x18000
	v_add_u32_e32 v136, s51, v154
	s_add_i32 s64, 0, 0x1c000
	ds_read_b128 v[148:151], v136
	ds_read_b128 v[160:163], v136 offset:1024
	ds_read_b128 v[164:167], v136 offset:2048
	ds_read_b128 v[168:171], v136 offset:3072
	v_add_u32_e32 v136, s64, v154
	ds_read_b128 v[172:175], v136
	ds_read_b128 v[176:179], v136 offset:1024
	ds_read_b128 v[180:183], v136 offset:2048
	ds_read_b128 v[184:187], v136 offset:3072
	s_add_u32 s46, s46, 0x40000
	s_addc_u32 s47, s47, 0
	s_mov_b32 m0, s22
	v_lshl_add_u64 v[230:231], s[46:47], 0, v[128:129]
	ds_read_b128 v[188:191], v157 offset:32768
	ds_read_b128 v[194:197], v157 offset:33792
	ds_read_b128 v[198:201], v157 offset:34816
	ds_read_b128 v[202:205], v157 offset:35840
	ds_read_b128 v[206:209], v157 offset:36864
	ds_read_b128 v[210:213], v157 offset:37888
	ds_read_b128 v[214:217], v157 offset:38912
	ds_read_b128 v[218:221], v157 offset:39936
	global_load_lds_dwordx4 v[230:231], off
	v_lshl_add_u64 v[230:231], s[46:47], 0, v[132:133]
	s_mov_b32 m0, s23
	s_nop 0
	global_load_lds_dwordx4 v[230:231], off
	s_waitcnt vmcnt(8)
	s_waitcnt lgkmcnt(0)
	s_barrier
	s_waitcnt lgkmcnt(0)
	v_mfma_f32_16x16x32_bf16 v[124:127], v[148:151], v[188:191], v[124:127]
	v_mfma_f32_16x16x32_bf16 v[120:123], v[164:167], v[188:191], v[120:123]
	v_mfma_f32_16x16x32_bf16 v[108:111], v[148:151], v[198:201], v[108:111]
	v_mfma_f32_16x16x32_bf16 v[104:107], v[164:167], v[198:201], v[104:107]
	v_mfma_f32_16x16x32_bf16 v[96:99], v[148:151], v[206:209], v[96:99]
	v_mfma_f32_16x16x32_bf16 v[88:91], v[164:167], v[206:209], v[88:91]
	v_mfma_f32_16x16x32_bf16 v[84:87], v[148:151], v[214:217], v[84:87]
	v_mfma_f32_16x16x32_bf16 v[76:79], v[164:167], v[214:217], v[76:79]
	v_mfma_f32_16x16x32_bf16 v[124:127], v[160:163], v[194:197], v[124:127]
	v_mfma_f32_16x16x32_bf16 v[120:123], v[168:171], v[194:197], v[120:123]
	v_mfma_f32_16x16x32_bf16 v[108:111], v[160:163], v[202:205], v[108:111]
	v_mfma_f32_16x16x32_bf16 v[104:107], v[168:171], v[202:205], v[104:107]
	v_mfma_f32_16x16x32_bf16 v[96:99], v[160:163], v[210:213], v[96:99]
	v_mfma_f32_16x16x32_bf16 v[88:91], v[168:171], v[210:213], v[88:91]
	v_mfma_f32_16x16x32_bf16 v[84:87], v[160:163], v[218:221], v[84:87]
	v_mfma_f32_16x16x32_bf16 v[76:79], v[168:171], v[218:221], v[76:79]
	v_mfma_f32_16x16x32_bf16 v[116:119], v[172:175], v[188:191], v[116:119]
	v_mfma_f32_16x16x32_bf16 v[112:115], v[180:183], v[188:191], v[112:115]
	v_mfma_f32_16x16x32_bf16 v[100:103], v[172:175], v[198:201], v[100:103]
	v_mfma_f32_16x16x32_bf16 v[92:95], v[180:183], v[198:201], v[92:95]
	v_mfma_f32_16x16x32_bf16 v[80:83], v[172:175], v[206:209], v[80:83]
	v_mfma_f32_16x16x32_bf16 v[72:75], v[180:183], v[206:209], v[72:75]
	v_mfma_f32_16x16x32_bf16 v[68:71], v[172:175], v[214:217], v[68:71]
	v_mfma_f32_16x16x32_bf16 v[64:67], v[180:183], v[214:217], v[64:67]
	v_mfma_f32_16x16x32_bf16 v[116:119], v[176:179], v[194:197], v[116:119]
	v_mfma_f32_16x16x32_bf16 v[112:115], v[184:187], v[194:197], v[112:115]
	v_mfma_f32_16x16x32_bf16 v[100:103], v[176:179], v[202:205], v[100:103]
	v_mfma_f32_16x16x32_bf16 v[92:95], v[184:187], v[202:205], v[92:95]
	v_mfma_f32_16x16x32_bf16 v[80:83], v[176:179], v[210:213], v[80:83]
	v_mfma_f32_16x16x32_bf16 v[72:75], v[184:187], v[210:213], v[72:75]
	v_mfma_f32_16x16x32_bf16 v[68:71], v[176:179], v[218:221], v[68:71]
	v_mfma_f32_16x16x32_bf16 v[64:67], v[184:187], v[218:221], v[64:67]
	s_barrier
	s_add_i32 s46, s51, s15
	v_lshl_add_u64 v[222:223], v[222:223], 0, s[18:19]
	s_mov_b32 m0, s46
	ds_read_b128 v[188:191], v157 offset:49152
	ds_read_b128 v[194:197], v157 offset:50176
	ds_read_b128 v[198:201], v157 offset:51200
	ds_read_b128 v[202:205], v157 offset:52224
	ds_read_b128 v[206:209], v157 offset:53248
	ds_read_b128 v[210:213], v157 offset:54272
	ds_read_b128 v[214:217], v157 offset:55296
	ds_read_b128 v[218:221], v157 offset:56320
	global_load_lds_dwordx4 v[222:223], off
	s_add_i32 m0, s46, 0x2000
	s_add_u32 s44, s44, 0x40080
	v_lshl_add_u64 v[222:223], v[224:225], 0, s[18:19]
	s_addc_u32 s45, s45, 0
	s_add_i32 s46, s64, s15
	global_load_lds_dwordx4 v[222:223], off
	v_lshl_add_u64 v[222:223], s[44:45], 0, v[130:131]
	s_mov_b32 m0, s46
	s_nop 0
	global_load_lds_dwordx4 v[222:223], off
	v_lshl_add_u64 v[222:223], s[44:45], 0, v[134:135]
	s_add_i32 m0, s46, 0x2000
	s_nop 0
	global_load_lds_dwordx4 v[222:223], off
	v_lshl_add_u64 v[222:223], v[226:227], 0, s[18:19]
	s_mov_b32 m0, s70
	s_nop 0
	global_load_lds_dwordx4 v[222:223], off
	v_lshl_add_u64 v[222:223], v[228:229], 0, s[18:19]
	s_mov_b32 m0, s71
	s_nop 0
	global_load_lds_dwordx4 v[222:223], off
	s_waitcnt vmcnt(8)
	s_waitcnt lgkmcnt(0)
	s_barrier
	s_waitcnt lgkmcnt(0)
	v_mfma_f32_16x16x32_bf16 v[60:63], v[148:151], v[188:191], v[60:63]
	v_mfma_f32_16x16x32_bf16 v[56:59], v[164:167], v[188:191], v[56:59]
	v_mfma_f32_16x16x32_bf16 v[44:47], v[148:151], v[198:201], v[44:47]
	v_mfma_f32_16x16x32_bf16 v[40:43], v[164:167], v[198:201], v[40:43]
	v_mfma_f32_16x16x32_bf16 v[32:35], v[148:151], v[206:209], v[32:35]
	v_mfma_f32_16x16x32_bf16 v[24:27], v[164:167], v[206:209], v[24:27]
	v_mfma_f32_16x16x32_bf16 v[20:23], v[148:151], v[214:217], v[20:23]
	v_mfma_f32_16x16x32_bf16 v[12:15], v[164:167], v[214:217], v[12:15]
	v_mfma_f32_16x16x32_bf16 v[60:63], v[160:163], v[194:197], v[60:63]
	v_mfma_f32_16x16x32_bf16 v[56:59], v[168:171], v[194:197], v[56:59]
	v_mfma_f32_16x16x32_bf16 v[44:47], v[160:163], v[202:205], v[44:47]
	v_mfma_f32_16x16x32_bf16 v[40:43], v[168:171], v[202:205], v[40:43]
	v_mfma_f32_16x16x32_bf16 v[32:35], v[160:163], v[210:213], v[32:35]
	v_mfma_f32_16x16x32_bf16 v[24:27], v[168:171], v[210:213], v[24:27]
	v_mfma_f32_16x16x32_bf16 v[20:23], v[160:163], v[218:221], v[20:23]
	v_mfma_f32_16x16x32_bf16 v[12:15], v[168:171], v[218:221], v[12:15]
	v_mfma_f32_16x16x32_bf16 v[52:55], v[172:175], v[188:191], v[52:55]
	v_mfma_f32_16x16x32_bf16 v[48:51], v[180:183], v[188:191], v[48:51]
	v_mfma_f32_16x16x32_bf16 v[36:39], v[172:175], v[198:201], v[36:39]
	v_mfma_f32_16x16x32_bf16 v[28:31], v[180:183], v[198:201], v[28:31]
	v_mfma_f32_16x16x32_bf16 v[16:19], v[172:175], v[206:209], v[16:19]
	v_mfma_f32_16x16x32_bf16 v[8:11], v[180:183], v[206:209], v[8:11]
	v_mfma_f32_16x16x32_bf16 v[4:7], v[172:175], v[214:217], v[4:7]
	v_mfma_f32_16x16x32_bf16 v[0:3], v[180:183], v[214:217], v[0:3]
	v_mfma_f32_16x16x32_bf16 v[52:55], v[176:179], v[194:197], v[52:55]
	v_mfma_f32_16x16x32_bf16 v[48:51], v[184:187], v[194:197], v[48:51]
	v_mfma_f32_16x16x32_bf16 v[36:39], v[176:179], v[202:205], v[36:39]
	v_mfma_f32_16x16x32_bf16 v[28:31], v[184:187], v[202:205], v[28:31]
	v_mfma_f32_16x16x32_bf16 v[16:19], v[176:179], v[210:213], v[16:19]
	v_mfma_f32_16x16x32_bf16 v[8:11], v[184:187], v[210:213], v[8:11]
	v_mfma_f32_16x16x32_bf16 v[4:7], v[176:179], v[218:221], v[4:7]
	v_mfma_f32_16x16x32_bf16 v[0:3], v[184:187], v[218:221], v[0:3]
	s_barrier
	s_add_i32 s50, s50, 2
	s_add_u32 s8, s8, 0x100
	s_addc_u32 s9, s9, 0
	s_add_u32 s48, s48, 0x100
	s_addc_u32 s49, s49, 0
	s_cmp_gt_u32 s50, 13
	s_cbranch_scc1 .Lpeel_x0

.LBB0_639:
	s_ashr_i32 s13, s12, 31
	s_lshl_b64 s[16:17], s[12:13], 19
	s_add_u32 s16, s74, s16
	s_addc_u32 s17, s75, s17
	s_and_b64 s[18:19], s[38:39], exec
	s_cselect_b32 s13, s17, s37
	s_cselect_b32 s67, s16, s36
	s_ashr_i32 s11, s10, 31
	s_lshl_b64 s[18:19], s[10:11], 19
	s_add_u32 s18, s15, s18
	s_addc_u32 s19, s20, s19
	s_and_b64 s[46:47], s[38:39], exec
	s_cselect_b32 s11, s19, s43
	s_cselect_b32 s68, s18, s42
	s_add_u32 s36, s36, 0x40080
	s_addc_u32 s37, s37, 0
	s_add_u32 s69, s42, 0x100
	s_addc_u32 s70, s43, 0
	s_mov_b32 s71, -2
	s_nop 0
	s_nop 0
	s_nop 0
	s_nop 0
	s_nop 0
	ds_read_b128 v[170:173], v164
	ds_read_b128 v[174:177], v164 offset:1024
	ds_read_b128 v[178:181], v164 offset:2048
	ds_read_b128 v[182:185], v164 offset:3072
	ds_read_b128 v[186:189], v165
	ds_read_b128 v[194:197], v165 offset:1024
	ds_read_b128 v[198:201], v165 offset:2048
	ds_read_b128 v[202:205], v165 offset:3072
	s_add_u32 s42, s36, 0xfffc0080
	s_addc_u32 s43, s37, -1
	s_cmp_eq_u32 s71, 12
	s_cselect_b32 s47, s13, s43
	s_cselect_b32 s46, s67, s42
	s_cselect_b32 s43, s11, s70
	s_cselect_b32 s42, s68, s69
	v_lshl_add_u64 v[148:149], s[36:37], 0, v[138:139]
	s_add_i32 m0, s22, 0xc000
	ds_read_b128 v[206:209], v166
	ds_read_b128 v[210:213], v166 offset:1024
	ds_read_b128 v[214:217], v166 offset:2048
	ds_read_b128 v[218:221], v166 offset:3072
	ds_read_b128 v[222:225], v166 offset:4096
	ds_read_b128 v[226:229], v166 offset:5120
	ds_read_b128 v[230:233], v166 offset:6144
	ds_read_b128 v[234:237], v166 offset:7168
	global_load_lds_dwordx4 v[148:149], off
	v_lshl_add_u64 v[148:149], s[36:37], 0, v[140:141]
	s_add_i32 m0, s22, 0xe000
	s_nop 0
	global_load_lds_dwordx4 v[148:149], off
	s_waitcnt vmcnt(8)
	s_waitcnt lgkmcnt(0)
	s_barrier
	s_waitcnt lgkmcnt(0)
	v_mfma_f32_16x16x32_bf16 v[124:127], v[170:173], v[206:209], 0
	v_mfma_f32_16x16x32_bf16 v[120:123], v[178:181], v[206:209], 0
	v_mfma_f32_16x16x32_bf16 v[116:119], v[170:173], v[214:217], 0
	v_mfma_f32_16x16x32_bf16 v[112:115], v[178:181], v[214:217], 0
	v_mfma_f32_16x16x32_bf16 v[100:103], v[170:173], v[222:225], 0
	v_mfma_f32_16x16x32_bf16 v[96:99], v[178:181], v[222:225], 0
	v_mfma_f32_16x16x32_bf16 v[84:87], v[170:173], v[230:233], 0
	v_mfma_f32_16x16x32_bf16 v[80:83], v[178:181], v[230:233], 0
	v_mfma_f32_16x16x32_bf16 v[124:127], v[174:177], v[210:213], v[124:127]
	v_mfma_f32_16x16x32_bf16 v[120:123], v[182:185], v[210:213], v[120:123]
	v_mfma_f32_16x16x32_bf16 v[116:119], v[174:177], v[218:221], v[116:119]
	v_mfma_f32_16x16x32_bf16 v[112:115], v[182:185], v[218:221], v[112:115]
	v_mfma_f32_16x16x32_bf16 v[100:103], v[174:177], v[226:229], v[100:103]
	v_mfma_f32_16x16x32_bf16 v[96:99], v[182:185], v[226:229], v[96:99]
	v_mfma_f32_16x16x32_bf16 v[84:87], v[174:177], v[234:237], v[84:87]
	v_mfma_f32_16x16x32_bf16 v[80:83], v[182:185], v[234:237], v[80:83]
	v_mfma_f32_16x16x32_bf16 v[108:111], v[186:189], v[206:209], 0
	v_mfma_f32_16x16x32_bf16 v[104:107], v[198:201], v[206:209], 0
	v_mfma_f32_16x16x32_bf16 v[92:95], v[186:189], v[214:217], 0
	v_mfma_f32_16x16x32_bf16 v[88:91], v[198:201], v[214:217], 0
	v_mfma_f32_16x16x32_bf16 v[76:79], v[186:189], v[222:225], 0
	v_mfma_f32_16x16x32_bf16 v[72:75], v[198:201], v[222:225], 0
	v_mfma_f32_16x16x32_bf16 v[68:71], v[186:189], v[230:233], 0
	v_mfma_f32_16x16x32_bf16 v[64:67], v[198:201], v[230:233], 0
	v_mfma_f32_16x16x32_bf16 v[108:111], v[194:197], v[210:213], v[108:111]
	v_mfma_f32_16x16x32_bf16 v[104:107], v[202:205], v[210:213], v[104:107]
	v_mfma_f32_16x16x32_bf16 v[92:95], v[194:197], v[218:221], v[92:95]
	v_mfma_f32_16x16x32_bf16 v[88:91], v[202:205], v[218:221], v[88:91]
	v_mfma_f32_16x16x32_bf16 v[76:79], v[194:197], v[226:229], v[76:79]
	v_mfma_f32_16x16x32_bf16 v[72:75], v[202:205], v[226:229], v[72:75]
	v_mfma_f32_16x16x32_bf16 v[68:71], v[194:197], v[234:237], v[68:71]
	v_mfma_f32_16x16x32_bf16 v[64:67], v[202:205], v[234:237], v[64:67]
	s_barrier
	s_add_i32 s72, s65, s14
	v_lshl_add_u64 v[148:149], s[42:43], 0, v[132:133]
	s_mov_b32 m0, s72
	ds_read_b128 v[206:209], v166 offset:16384
	ds_read_b128 v[210:213], v166 offset:17408
	ds_read_b128 v[214:217], v166 offset:18432
	ds_read_b128 v[218:221], v166 offset:19456
	ds_read_b128 v[222:225], v166 offset:20480
	ds_read_b128 v[226:229], v166 offset:21504
	ds_read_b128 v[230:233], v166 offset:22528
	ds_read_b128 v[234:237], v166 offset:23552
	global_load_lds_dwordx4 v[148:149], off
	s_add_i32 m0, s72, 0x2000
	s_add_u32 s72, s42, 0x40000
	v_lshl_add_u64 v[190:191], s[42:43], 0, v[128:129]
	s_addc_u32 s73, s43, 0
	s_add_i32 s78, s66, s14
	global_load_lds_dwordx4 v[190:191], off
	v_lshl_add_u64 v[238:239], s[72:73], 0, v[132:133]
	s_mov_b32 m0, s78
	v_lshl_add_u64 v[240:241], s[46:47], 0, v[130:131]
	global_load_lds_dwordx4 v[238:239], off
	v_lshl_add_u64 v[238:239], s[72:73], 0, v[128:129]
	s_add_i32 m0, s78, 0x2000
	s_nop 0
	global_load_lds_dwordx4 v[238:239], off
	v_lshl_add_u64 v[238:239], s[46:47], 0, v[134:135]
	s_mov_b32 m0, s22
	s_nop 0
	global_load_lds_dwordx4 v[238:239], off
	s_mov_b32 m0, s23
	s_nop 0
	global_load_lds_dwordx4 v[240:241], off
	s_waitcnt vmcnt(8)
	s_waitcnt lgkmcnt(0)
	s_barrier
	s_waitcnt lgkmcnt(0)
	v_mfma_f32_16x16x32_bf16 v[60:63], v[170:173], v[206:209], 0
	v_mfma_f32_16x16x32_bf16 v[56:59], v[178:181], v[206:209], 0
	v_mfma_f32_16x16x32_bf16 v[52:55], v[170:173], v[214:217], 0
	v_mfma_f32_16x16x32_bf16 v[48:51], v[178:181], v[214:217], 0
	v_mfma_f32_16x16x32_bf16 v[36:39], v[170:173], v[222:225], 0
	v_mfma_f32_16x16x32_bf16 v[32:35], v[178:181], v[222:225], 0
	v_mfma_f32_16x16x32_bf16 v[20:23], v[170:173], v[230:233], 0
	v_mfma_f32_16x16x32_bf16 v[16:19], v[178:181], v[230:233], 0
	v_mfma_f32_16x16x32_bf16 v[60:63], v[174:177], v[210:213], v[60:63]
	v_mfma_f32_16x16x32_bf16 v[56:59], v[182:185], v[210:213], v[56:59]
	v_mfma_f32_16x16x32_bf16 v[52:55], v[174:177], v[218:221], v[52:55]
	v_mfma_f32_16x16x32_bf16 v[48:51], v[182:185], v[218:221], v[48:51]
	v_mfma_f32_16x16x32_bf16 v[36:39], v[174:177], v[226:229], v[36:39]
	v_mfma_f32_16x16x32_bf16 v[32:35], v[182:185], v[226:229], v[32:35]
	v_mfma_f32_16x16x32_bf16 v[20:23], v[174:177], v[234:237], v[20:23]
	v_mfma_f32_16x16x32_bf16 v[16:19], v[182:185], v[234:237], v[16:19]
	v_mfma_f32_16x16x32_bf16 v[44:47], v[186:189], v[206:209], 0
	v_mfma_f32_16x16x32_bf16 v[40:43], v[198:201], v[206:209], 0
	v_mfma_f32_16x16x32_bf16 v[28:31], v[186:189], v[214:217], 0
	v_mfma_f32_16x16x32_bf16 v[24:27], v[198:201], v[214:217], 0
	v_mfma_f32_16x16x32_bf16 v[12:15], v[186:189], v[222:225], 0
	v_mfma_f32_16x16x32_bf16 v[8:11], v[198:201], v[222:225], 0
	v_mfma_f32_16x16x32_bf16 v[4:7], v[186:189], v[230:233], 0
	v_mfma_f32_16x16x32_bf16 v[0:3], v[198:201], v[230:233], 0
	v_mfma_f32_16x16x32_bf16 v[44:47], v[194:197], v[210:213], v[44:47]
	v_mfma_f32_16x16x32_bf16 v[40:43], v[202:205], v[210:213], v[40:43]
	v_mfma_f32_16x16x32_bf16 v[28:31], v[194:197], v[218:221], v[28:31]
	v_mfma_f32_16x16x32_bf16 v[24:27], v[202:205], v[218:221], v[24:27]
	v_mfma_f32_16x16x32_bf16 v[12:15], v[194:197], v[226:229], v[12:15]
	v_mfma_f32_16x16x32_bf16 v[8:11], v[202:205], v[226:229], v[8:11]
	v_mfma_f32_16x16x32_bf16 v[4:7], v[194:197], v[234:237], v[4:7]
	v_mfma_f32_16x16x32_bf16 v[0:3], v[202:205], v[234:237], v[0:3]
	s_barrier
	s_add_i32 s72, 0, 0x18000
	v_add_u32_e32 v136, s72, v152
	s_add_i32 s73, 0, 0x1c000
	ds_read_b128 v[170:173], v136
	ds_read_b128 v[174:177], v136 offset:1024
	ds_read_b128 v[178:181], v136 offset:2048
	ds_read_b128 v[182:185], v136 offset:3072
	v_add_u32_e32 v136, s73, v152
	ds_read_b128 v[186:189], v136
	ds_read_b128 v[194:197], v136 offset:1024
	ds_read_b128 v[198:201], v136 offset:2048
	ds_read_b128 v[202:205], v136 offset:3072
	s_add_u32 s46, s46, 0x40000
	s_addc_u32 s47, s47, 0
	s_mov_b32 m0, s33
	v_lshl_add_u64 v[242:243], s[46:47], 0, v[134:135]
	ds_read_b128 v[206:209], v166 offset:32768
	ds_read_b128 v[210:213], v166 offset:33792
	ds_read_b128 v[214:217], v166 offset:34816
	ds_read_b128 v[218:221], v166 offset:35840
	ds_read_b128 v[222:225], v166 offset:36864
	ds_read_b128 v[226:229], v166 offset:37888
	ds_read_b128 v[230:233], v166 offset:38912
	ds_read_b128 v[234:237], v166 offset:39936
	global_load_lds_dwordx4 v[242:243], off
	v_lshl_add_u64 v[242:243], s[46:47], 0, v[130:131]
	s_mov_b32 m0, s48
	s_nop 0
	global_load_lds_dwordx4 v[242:243], off
	s_waitcnt vmcnt(8)
	s_waitcnt lgkmcnt(0)
	s_barrier
	s_waitcnt lgkmcnt(0)
	v_mfma_f32_16x16x32_bf16 v[124:127], v[170:173], v[206:209], v[124:127]
	v_mfma_f32_16x16x32_bf16 v[120:123], v[178:181], v[206:209], v[120:123]
	v_mfma_f32_16x16x32_bf16 v[116:119], v[170:173], v[214:217], v[116:119]
	v_mfma_f32_16x16x32_bf16 v[112:115], v[178:181], v[214:217], v[112:115]
	v_mfma_f32_16x16x32_bf16 v[100:103], v[170:173], v[222:225], v[100:103]
	v_mfma_f32_16x16x32_bf16 v[96:99], v[178:181], v[222:225], v[96:99]
	v_mfma_f32_16x16x32_bf16 v[84:87], v[170:173], v[230:233], v[84:87]
	v_mfma_f32_16x16x32_bf16 v[80:83], v[178:181], v[230:233], v[80:83]
	v_mfma_f32_16x16x32_bf16 v[124:127], v[174:177], v[210:213], v[124:127]
	v_mfma_f32_16x16x32_bf16 v[120:123], v[182:185], v[210:213], v[120:123]
	v_mfma_f32_16x16x32_bf16 v[116:119], v[174:177], v[218:221], v[116:119]
	v_mfma_f32_16x16x32_bf16 v[112:115], v[182:185], v[218:221], v[112:115]
	v_mfma_f32_16x16x32_bf16 v[100:103], v[174:177], v[226:229], v[100:103]
	v_mfma_f32_16x16x32_bf16 v[96:99], v[182:185], v[226:229], v[96:99]
	v_mfma_f32_16x16x32_bf16 v[84:87], v[174:177], v[234:237], v[84:87]
	v_mfma_f32_16x16x32_bf16 v[80:83], v[182:185], v[234:237], v[80:83]
	v_mfma_f32_16x16x32_bf16 v[108:111], v[186:189], v[206:209], v[108:111]
	v_mfma_f32_16x16x32_bf16 v[104:107], v[198:201], v[206:209], v[104:107]
	v_mfma_f32_16x16x32_bf16 v[92:95], v[186:189], v[214:217], v[92:95]
	v_mfma_f32_16x16x32_bf16 v[88:91], v[198:201], v[214:217], v[88:91]
	v_mfma_f32_16x16x32_bf16 v[76:79], v[186:189], v[222:225], v[76:79]
	v_mfma_f32_16x16x32_bf16 v[72:75], v[198:201], v[222:225], v[72:75]
	v_mfma_f32_16x16x32_bf16 v[68:71], v[186:189], v[230:233], v[68:71]
	v_mfma_f32_16x16x32_bf16 v[64:67], v[198:201], v[230:233], v[64:67]
	v_mfma_f32_16x16x32_bf16 v[108:111], v[194:197], v[210:213], v[108:111]
	v_mfma_f32_16x16x32_bf16 v[104:107], v[202:205], v[210:213], v[104:107]
	v_mfma_f32_16x16x32_bf16 v[92:95], v[194:197], v[218:221], v[92:95]
	v_mfma_f32_16x16x32_bf16 v[88:91], v[202:205], v[218:221], v[88:91]
	v_mfma_f32_16x16x32_bf16 v[76:79], v[194:197], v[226:229], v[76:79]
	v_mfma_f32_16x16x32_bf16 v[72:75], v[202:205], v[226:229], v[72:75]
	v_mfma_f32_16x16x32_bf16 v[68:71], v[194:197], v[234:237], v[68:71]
	v_mfma_f32_16x16x32_bf16 v[64:67], v[202:205], v[234:237], v[64:67]
	s_barrier
	s_add_i32 s46, s72, s14
	v_lshl_add_u64 v[148:149], v[148:149], 0, s[4:5]
	s_mov_b32 m0, s46
	ds_read_b128 v[206:209], v166 offset:49152
	ds_read_b128 v[210:213], v166 offset:50176
	ds_read_b128 v[214:217], v166 offset:51200
	ds_read_b128 v[218:221], v166 offset:52224
	ds_read_b128 v[222:225], v166 offset:53248
	ds_read_b128 v[226:229], v166 offset:54272
	ds_read_b128 v[230:233], v166 offset:55296
	ds_read_b128 v[234:237], v166 offset:56320
	global_load_lds_dwordx4 v[148:149], off
	s_add_i32 m0, s46, 0x2000
	s_add_u32 s42, s42, 0x40080
	v_lshl_add_u64 v[148:149], v[190:191], 0, s[4:5]
	s_addc_u32 s43, s43, 0
	s_add_i32 s46, s73, s14
	global_load_lds_dwordx4 v[148:149], off
	v_lshl_add_u64 v[148:149], s[42:43], 0, v[132:133]
	s_mov_b32 m0, s46
	s_nop 0
	global_load_lds_dwordx4 v[148:149], off
	v_lshl_add_u64 v[148:149], s[42:43], 0, v[128:129]
	s_add_i32 m0, s46, 0x2000
	s_nop 0
	global_load_lds_dwordx4 v[148:149], off
	v_lshl_add_u64 v[148:149], v[238:239], 0, s[4:5]
	s_mov_b32 m0, s50
	s_nop 0
	global_load_lds_dwordx4 v[148:149], off
	v_lshl_add_u64 v[148:149], v[240:241], 0, s[4:5]
	s_mov_b32 m0, s51
	s_nop 0
	global_load_lds_dwordx4 v[148:149], off
	s_waitcnt vmcnt(8)
	s_waitcnt lgkmcnt(0)
	s_barrier
	s_waitcnt lgkmcnt(0)
	v_mfma_f32_16x16x32_bf16 v[60:63], v[170:173], v[206:209], v[60:63]
	v_mfma_f32_16x16x32_bf16 v[56:59], v[178:181], v[206:209], v[56:59]
	v_mfma_f32_16x16x32_bf16 v[52:55], v[170:173], v[214:217], v[52:55]
	v_mfma_f32_16x16x32_bf16 v[48:51], v[178:181], v[214:217], v[48:51]
	v_mfma_f32_16x16x32_bf16 v[36:39], v[170:173], v[222:225], v[36:39]
	v_mfma_f32_16x16x32_bf16 v[32:35], v[178:181], v[222:225], v[32:35]
	v_mfma_f32_16x16x32_bf16 v[20:23], v[170:173], v[230:233], v[20:23]
	v_mfma_f32_16x16x32_bf16 v[16:19], v[178:181], v[230:233], v[16:19]
	v_mfma_f32_16x16x32_bf16 v[60:63], v[174:177], v[210:213], v[60:63]
	v_mfma_f32_16x16x32_bf16 v[56:59], v[182:185], v[210:213], v[56:59]
	v_mfma_f32_16x16x32_bf16 v[52:55], v[174:177], v[218:221], v[52:55]
	v_mfma_f32_16x16x32_bf16 v[48:51], v[182:185], v[218:221], v[48:51]
	v_mfma_f32_16x16x32_bf16 v[36:39], v[174:177], v[226:229], v[36:39]
	v_mfma_f32_16x16x32_bf16 v[32:35], v[182:185], v[226:229], v[32:35]
	v_mfma_f32_16x16x32_bf16 v[20:23], v[174:177], v[234:237], v[20:23]
	v_mfma_f32_16x16x32_bf16 v[16:19], v[182:185], v[234:237], v[16:19]
	v_mfma_f32_16x16x32_bf16 v[44:47], v[186:189], v[206:209], v[44:47]
	v_mfma_f32_16x16x32_bf16 v[40:43], v[198:201], v[206:209], v[40:43]
	v_mfma_f32_16x16x32_bf16 v[28:31], v[186:189], v[214:217], v[28:31]
	v_mfma_f32_16x16x32_bf16 v[24:27], v[198:201], v[214:217], v[24:27]
	v_mfma_f32_16x16x32_bf16 v[12:15], v[186:189], v[222:225], v[12:15]
	v_mfma_f32_16x16x32_bf16 v[8:11], v[198:201], v[222:225], v[8:11]
	v_mfma_f32_16x16x32_bf16 v[4:7], v[186:189], v[230:233], v[4:7]
	v_mfma_f32_16x16x32_bf16 v[0:3], v[198:201], v[230:233], v[0:3]
	v_mfma_f32_16x16x32_bf16 v[44:47], v[194:197], v[210:213], v[44:47]
	v_mfma_f32_16x16x32_bf16 v[40:43], v[202:205], v[210:213], v[40:43]
	v_mfma_f32_16x16x32_bf16 v[28:31], v[194:197], v[218:221], v[28:31]
	v_mfma_f32_16x16x32_bf16 v[24:27], v[202:205], v[218:221], v[24:27]
	v_mfma_f32_16x16x32_bf16 v[12:15], v[194:197], v[226:229], v[12:15]
	v_mfma_f32_16x16x32_bf16 v[8:11], v[202:205], v[226:229], v[8:11]
	v_mfma_f32_16x16x32_bf16 v[4:7], v[194:197], v[234:237], v[4:7]
	v_mfma_f32_16x16x32_bf16 v[0:3], v[202:205], v[234:237], v[0:3]
	s_barrier
	s_add_i32 s71, s71, 2
	s_add_u32 s36, s36, 0x100
	s_addc_u32 s37, s37, 0
	s_add_u32 s69, s69, 0x100
	s_addc_u32 s70, s70, 0
	s_cmp_gt_u32 s71, 13
	s_cbranch_scc1 .Lpeel_x1

.LBB0_676:
	s_ashr_i32 s13, s12, 31
	s_lshl_b64 s[16:17], s[12:13], 19
	s_add_u32 s16, s15, s16
	s_addc_u32 s17, s20, s17
	s_and_b64 s[18:19], s[38:39], exec
	s_cselect_b32 s13, s17, s37
	s_cselect_b32 s53, s16, s36
	s_ashr_i32 s11, s10, 31
	s_lshl_b64 s[18:19], s[10:11], 19
	s_add_u32 s18, s74, s18
	s_addc_u32 s19, s75, s19
	s_and_b64 s[46:47], s[38:39], exec
	s_cselect_b32 s11, s19, s43
	s_cselect_b32 s64, s18, s42
	s_add_u32 s36, s36, 0x40080
	s_addc_u32 s37, s37, 0
	s_add_u32 s65, s42, 0x100
	s_addc_u32 s66, s43, 0
	s_mov_b32 s67, -2
	s_nop 0
	s_nop 0
	s_nop 0
	s_nop 0
	s_nop 0
	ds_read_b128 v[150:153], v147
	ds_read_b128 v[154:157], v147 offset:1024
	ds_read_b128 v[158:161], v147 offset:2048
	ds_read_b128 v[162:165], v147 offset:3072
	ds_read_b128 v[166:169], v148
	ds_read_b128 v[170:173], v148 offset:1024
	ds_read_b128 v[174:177], v148 offset:2048
	ds_read_b128 v[178:181], v148 offset:3072
	s_add_u32 s42, s36, 0xfffc0080
	s_addc_u32 s43, s37, -1
	s_cmp_eq_u32 s67, 12
	s_cselect_b32 s47, s13, s43
	s_cselect_b32 s46, s53, s42
	s_cselect_b32 s43, s11, s66
	s_cselect_b32 s42, s64, s65
	v_lshl_add_u64 v[190:191], s[36:37], 0, v[136:137]
	s_add_i32 m0, s21, 0xc000
	ds_read_b128 v[182:185], v149
	ds_read_b128 v[186:189], v149 offset:1024
	ds_read_b128 v[194:197], v149 offset:2048
	ds_read_b128 v[198:201], v149 offset:3072
	ds_read_b128 v[202:205], v149 offset:4096
	ds_read_b128 v[206:209], v149 offset:5120
	ds_read_b128 v[210:213], v149 offset:6144
	ds_read_b128 v[214:217], v149 offset:7168
	global_load_lds_dwordx4 v[190:191], off
	v_lshl_add_u64 v[190:191], s[36:37], 0, v[138:139]
	s_add_i32 m0, s21, 0xe000
	s_nop 0
	global_load_lds_dwordx4 v[190:191], off
	s_waitcnt vmcnt(8)
	s_waitcnt lgkmcnt(0)
	s_barrier
	s_waitcnt lgkmcnt(0)
	v_mfma_f32_16x16x32_bf16 v[124:127], v[150:153], v[182:185], 0
	v_mfma_f32_16x16x32_bf16 v[120:123], v[158:161], v[182:185], 0
	v_mfma_f32_16x16x32_bf16 v[116:119], v[150:153], v[194:197], 0
	v_mfma_f32_16x16x32_bf16 v[112:115], v[158:161], v[194:197], 0
	v_mfma_f32_16x16x32_bf16 v[100:103], v[150:153], v[202:205], 0
	v_mfma_f32_16x16x32_bf16 v[96:99], v[158:161], v[202:205], 0
	v_mfma_f32_16x16x32_bf16 v[84:87], v[150:153], v[210:213], 0
	v_mfma_f32_16x16x32_bf16 v[80:83], v[158:161], v[210:213], 0
	v_mfma_f32_16x16x32_bf16 v[124:127], v[154:157], v[186:189], v[124:127]
	v_mfma_f32_16x16x32_bf16 v[120:123], v[162:165], v[186:189], v[120:123]
	v_mfma_f32_16x16x32_bf16 v[116:119], v[154:157], v[198:201], v[116:119]
	v_mfma_f32_16x16x32_bf16 v[112:115], v[162:165], v[198:201], v[112:115]
	v_mfma_f32_16x16x32_bf16 v[100:103], v[154:157], v[206:209], v[100:103]
	v_mfma_f32_16x16x32_bf16 v[96:99], v[162:165], v[206:209], v[96:99]
	v_mfma_f32_16x16x32_bf16 v[84:87], v[154:157], v[214:217], v[84:87]
	v_mfma_f32_16x16x32_bf16 v[80:83], v[162:165], v[214:217], v[80:83]
	v_mfma_f32_16x16x32_bf16 v[108:111], v[166:169], v[182:185], 0
	v_mfma_f32_16x16x32_bf16 v[104:107], v[174:177], v[182:185], 0
	v_mfma_f32_16x16x32_bf16 v[92:95], v[166:169], v[194:197], 0
	v_mfma_f32_16x16x32_bf16 v[88:91], v[174:177], v[194:197], 0
	v_mfma_f32_16x16x32_bf16 v[76:79], v[166:169], v[202:205], 0
	v_mfma_f32_16x16x32_bf16 v[72:75], v[174:177], v[202:205], 0
	v_mfma_f32_16x16x32_bf16 v[68:71], v[166:169], v[210:213], 0
	v_mfma_f32_16x16x32_bf16 v[64:67], v[174:177], v[210:213], 0
	v_mfma_f32_16x16x32_bf16 v[108:111], v[170:173], v[186:189], v[108:111]
	v_mfma_f32_16x16x32_bf16 v[104:107], v[178:181], v[186:189], v[104:107]
	v_mfma_f32_16x16x32_bf16 v[92:95], v[170:173], v[198:201], v[92:95]
	v_mfma_f32_16x16x32_bf16 v[88:91], v[178:181], v[198:201], v[88:91]
	v_mfma_f32_16x16x32_bf16 v[76:79], v[170:173], v[206:209], v[76:79]
	v_mfma_f32_16x16x32_bf16 v[72:75], v[178:181], v[206:209], v[72:75]
	v_mfma_f32_16x16x32_bf16 v[68:71], v[170:173], v[214:217], v[68:71]
	v_mfma_f32_16x16x32_bf16 v[64:67], v[178:181], v[214:217], v[64:67]
	s_barrier
	s_add_i32 s68, s51, s14
	v_lshl_add_u64 v[190:191], s[42:43], 0, v[132:133]
	s_mov_b32 m0, s68
	ds_read_b128 v[182:185], v149 offset:16384
	ds_read_b128 v[186:189], v149 offset:17408
	ds_read_b128 v[194:197], v149 offset:18432
	ds_read_b128 v[198:201], v149 offset:19456
	ds_read_b128 v[202:205], v149 offset:20480
	ds_read_b128 v[206:209], v149 offset:21504
	ds_read_b128 v[210:213], v149 offset:22528
	ds_read_b128 v[214:217], v149 offset:23552
	global_load_lds_dwordx4 v[190:191], off
	s_add_i32 m0, s68, 0x2000
	s_add_u32 s68, s42, 0x40000
	v_lshl_add_u64 v[218:219], s[42:43], 0, v[128:129]
	s_addc_u32 s69, s43, 0
	s_add_i32 s70, s52, s14
	global_load_lds_dwordx4 v[218:219], off
	v_lshl_add_u64 v[220:221], s[68:69], 0, v[132:133]
	s_mov_b32 m0, s70
	v_lshl_add_u64 v[222:223], s[46:47], 0, v[130:131]
	global_load_lds_dwordx4 v[220:221], off
	v_lshl_add_u64 v[220:221], s[68:69], 0, v[128:129]
	s_add_i32 m0, s70, 0x2000
	s_nop 0
	global_load_lds_dwordx4 v[220:221], off
	v_lshl_add_u64 v[220:221], s[46:47], 0, v[134:135]
	s_mov_b32 m0, s21
	s_nop 0
	global_load_lds_dwordx4 v[220:221], off
	s_mov_b32 m0, s22
	s_nop 0
	global_load_lds_dwordx4 v[222:223], off
	s_waitcnt vmcnt(8)
	s_waitcnt lgkmcnt(0)
	s_barrier
	s_waitcnt lgkmcnt(0)
	v_mfma_f32_16x16x32_bf16 v[60:63], v[150:153], v[182:185], 0
	v_mfma_f32_16x16x32_bf16 v[56:59], v[158:161], v[182:185], 0
	v_mfma_f32_16x16x32_bf16 v[52:55], v[150:153], v[194:197], 0
	v_mfma_f32_16x16x32_bf16 v[48:51], v[158:161], v[194:197], 0
	v_mfma_f32_16x16x32_bf16 v[36:39], v[150:153], v[202:205], 0
	v_mfma_f32_16x16x32_bf16 v[32:35], v[158:161], v[202:205], 0
	v_mfma_f32_16x16x32_bf16 v[20:23], v[150:153], v[210:213], 0
	v_mfma_f32_16x16x32_bf16 v[16:19], v[158:161], v[210:213], 0
	v_mfma_f32_16x16x32_bf16 v[60:63], v[154:157], v[186:189], v[60:63]
	v_mfma_f32_16x16x32_bf16 v[56:59], v[162:165], v[186:189], v[56:59]
	v_mfma_f32_16x16x32_bf16 v[52:55], v[154:157], v[198:201], v[52:55]
	v_mfma_f32_16x16x32_bf16 v[48:51], v[162:165], v[198:201], v[48:51]
	v_mfma_f32_16x16x32_bf16 v[36:39], v[154:157], v[206:209], v[36:39]
	v_mfma_f32_16x16x32_bf16 v[32:35], v[162:165], v[206:209], v[32:35]
	v_mfma_f32_16x16x32_bf16 v[20:23], v[154:157], v[214:217], v[20:23]
	v_mfma_f32_16x16x32_bf16 v[16:19], v[162:165], v[214:217], v[16:19]
	v_mfma_f32_16x16x32_bf16 v[44:47], v[166:169], v[182:185], 0
	v_mfma_f32_16x16x32_bf16 v[40:43], v[174:177], v[182:185], 0
	v_mfma_f32_16x16x32_bf16 v[28:31], v[166:169], v[194:197], 0
	v_mfma_f32_16x16x32_bf16 v[24:27], v[174:177], v[194:197], 0
	v_mfma_f32_16x16x32_bf16 v[12:15], v[166:169], v[202:205], 0
	v_mfma_f32_16x16x32_bf16 v[8:11], v[174:177], v[202:205], 0
	v_mfma_f32_16x16x32_bf16 v[4:7], v[166:169], v[210:213], 0
	v_mfma_f32_16x16x32_bf16 v[0:3], v[174:177], v[210:213], 0
	v_mfma_f32_16x16x32_bf16 v[44:47], v[170:173], v[186:189], v[44:47]
	v_mfma_f32_16x16x32_bf16 v[40:43], v[178:181], v[186:189], v[40:43]
	v_mfma_f32_16x16x32_bf16 v[28:31], v[170:173], v[198:201], v[28:31]
	v_mfma_f32_16x16x32_bf16 v[24:27], v[178:181], v[198:201], v[24:27]
	v_mfma_f32_16x16x32_bf16 v[12:15], v[170:173], v[206:209], v[12:15]
	v_mfma_f32_16x16x32_bf16 v[8:11], v[178:181], v[206:209], v[8:11]
	v_mfma_f32_16x16x32_bf16 v[4:7], v[170:173], v[214:217], v[4:7]
	v_mfma_f32_16x16x32_bf16 v[0:3], v[178:181], v[214:217], v[0:3]
	s_barrier
	s_add_i32 s68, 0, 0x18000
	s_add_i32 s69, 0, 0x1c000
	v_add_u32_e32 v162, s68, v145
	v_add_u32_e32 v178, s69, v145
	ds_read_b128 v[150:153], v162
	ds_read_b128 v[154:157], v162 offset:1024
	ds_read_b128 v[158:161], v162 offset:2048
	ds_read_b128 v[162:165], v162 offset:3072
	ds_read_b128 v[166:169], v178
	ds_read_b128 v[170:173], v178 offset:1024
	ds_read_b128 v[174:177], v178 offset:2048
	ds_read_b128 v[178:181], v178 offset:3072
	s_add_u32 s46, s46, 0x40000
	s_addc_u32 s47, s47, 0
	s_mov_b32 m0, s23
	v_lshl_add_u64 v[224:225], s[46:47], 0, v[134:135]
	ds_read_b128 v[182:185], v149 offset:32768
	ds_read_b128 v[186:189], v149 offset:33792
	ds_read_b128 v[194:197], v149 offset:34816
	ds_read_b128 v[198:201], v149 offset:35840
	ds_read_b128 v[202:205], v149 offset:36864
	ds_read_b128 v[206:209], v149 offset:37888
	ds_read_b128 v[210:213], v149 offset:38912
	ds_read_b128 v[214:217], v149 offset:39936
	global_load_lds_dwordx4 v[224:225], off
	v_lshl_add_u64 v[224:225], s[46:47], 0, v[130:131]
	s_mov_b32 m0, s33
	s_nop 0
	global_load_lds_dwordx4 v[224:225], off
	s_waitcnt vmcnt(8)
	s_waitcnt lgkmcnt(0)
	s_barrier
	s_waitcnt lgkmcnt(0)
	v_mfma_f32_16x16x32_bf16 v[124:127], v[150:153], v[182:185], v[124:127]
	v_mfma_f32_16x16x32_bf16 v[120:123], v[158:161], v[182:185], v[120:123]
	v_mfma_f32_16x16x32_bf16 v[116:119], v[150:153], v[194:197], v[116:119]
	v_mfma_f32_16x16x32_bf16 v[112:115], v[158:161], v[194:197], v[112:115]
	v_mfma_f32_16x16x32_bf16 v[100:103], v[150:153], v[202:205], v[100:103]
	v_mfma_f32_16x16x32_bf16 v[96:99], v[158:161], v[202:205], v[96:99]
	v_mfma_f32_16x16x32_bf16 v[84:87], v[150:153], v[210:213], v[84:87]
	v_mfma_f32_16x16x32_bf16 v[80:83], v[158:161], v[210:213], v[80:83]
	v_mfma_f32_16x16x32_bf16 v[124:127], v[154:157], v[186:189], v[124:127]
	v_mfma_f32_16x16x32_bf16 v[120:123], v[162:165], v[186:189], v[120:123]
	v_mfma_f32_16x16x32_bf16 v[116:119], v[154:157], v[198:201], v[116:119]
	v_mfma_f32_16x16x32_bf16 v[112:115], v[162:165], v[198:201], v[112:115]
	v_mfma_f32_16x16x32_bf16 v[100:103], v[154:157], v[206:209], v[100:103]
	v_mfma_f32_16x16x32_bf16 v[96:99], v[162:165], v[206:209], v[96:99]
	v_mfma_f32_16x16x32_bf16 v[84:87], v[154:157], v[214:217], v[84:87]
	v_mfma_f32_16x16x32_bf16 v[80:83], v[162:165], v[214:217], v[80:83]
	v_mfma_f32_16x16x32_bf16 v[108:111], v[166:169], v[182:185], v[108:111]
	v_mfma_f32_16x16x32_bf16 v[104:107], v[174:177], v[182:185], v[104:107]
	v_mfma_f32_16x16x32_bf16 v[92:95], v[166:169], v[194:197], v[92:95]
	v_mfma_f32_16x16x32_bf16 v[88:91], v[174:177], v[194:197], v[88:91]
	v_mfma_f32_16x16x32_bf16 v[76:79], v[166:169], v[202:205], v[76:79]
	v_mfma_f32_16x16x32_bf16 v[72:75], v[174:177], v[202:205], v[72:75]
	v_mfma_f32_16x16x32_bf16 v[68:71], v[166:169], v[210:213], v[68:71]
	v_mfma_f32_16x16x32_bf16 v[64:67], v[174:177], v[210:213], v[64:67]
	v_mfma_f32_16x16x32_bf16 v[108:111], v[170:173], v[186:189], v[108:111]
	v_mfma_f32_16x16x32_bf16 v[104:107], v[178:181], v[186:189], v[104:107]
	v_mfma_f32_16x16x32_bf16 v[92:95], v[170:173], v[198:201], v[92:95]
	v_mfma_f32_16x16x32_bf16 v[88:91], v[178:181], v[198:201], v[88:91]
	v_mfma_f32_16x16x32_bf16 v[76:79], v[170:173], v[206:209], v[76:79]
	v_mfma_f32_16x16x32_bf16 v[72:75], v[178:181], v[206:209], v[72:75]
	v_mfma_f32_16x16x32_bf16 v[68:71], v[170:173], v[214:217], v[68:71]
	v_mfma_f32_16x16x32_bf16 v[64:67], v[178:181], v[214:217], v[64:67]
	s_barrier
	s_add_i32 s46, s68, s14
	v_lshl_add_u64 v[190:191], v[190:191], 0, s[4:5]
	s_mov_b32 m0, s46
	ds_read_b128 v[182:185], v149 offset:49152
	ds_read_b128 v[186:189], v149 offset:50176
	ds_read_b128 v[194:197], v149 offset:51200
	ds_read_b128 v[198:201], v149 offset:52224
	ds_read_b128 v[202:205], v149 offset:53248
	ds_read_b128 v[206:209], v149 offset:54272
	ds_read_b128 v[210:213], v149 offset:55296
	ds_read_b128 v[214:217], v149 offset:56320
	global_load_lds_dwordx4 v[190:191], off
	s_add_i32 m0, s46, 0x2000
	s_add_u32 s42, s42, 0x40080
	v_lshl_add_u64 v[190:191], v[218:219], 0, s[4:5]
	s_addc_u32 s43, s43, 0
	s_add_i32 s46, s69, s14
	global_load_lds_dwordx4 v[190:191], off
	v_lshl_add_u64 v[190:191], s[42:43], 0, v[132:133]
	s_mov_b32 m0, s46
	s_nop 0
	global_load_lds_dwordx4 v[190:191], off
	v_lshl_add_u64 v[190:191], s[42:43], 0, v[128:129]
	s_add_i32 m0, s46, 0x2000
	s_nop 0
	global_load_lds_dwordx4 v[190:191], off
	v_lshl_add_u64 v[190:191], v[220:221], 0, s[4:5]
	s_mov_b32 m0, s49
	s_nop 0
	global_load_lds_dwordx4 v[190:191], off
	v_lshl_add_u64 v[190:191], v[222:223], 0, s[4:5]
	s_mov_b32 m0, s50
	s_nop 0
	global_load_lds_dwordx4 v[190:191], off
	s_waitcnt vmcnt(8)
	s_waitcnt lgkmcnt(0)
	s_barrier
	s_waitcnt lgkmcnt(0)
	v_mfma_f32_16x16x32_bf16 v[60:63], v[150:153], v[182:185], v[60:63]
	v_mfma_f32_16x16x32_bf16 v[56:59], v[158:161], v[182:185], v[56:59]
	v_mfma_f32_16x16x32_bf16 v[52:55], v[150:153], v[194:197], v[52:55]
	v_mfma_f32_16x16x32_bf16 v[48:51], v[158:161], v[194:197], v[48:51]
	v_mfma_f32_16x16x32_bf16 v[36:39], v[150:153], v[202:205], v[36:39]
	v_mfma_f32_16x16x32_bf16 v[32:35], v[158:161], v[202:205], v[32:35]
	v_mfma_f32_16x16x32_bf16 v[20:23], v[150:153], v[210:213], v[20:23]
	v_mfma_f32_16x16x32_bf16 v[16:19], v[158:161], v[210:213], v[16:19]
	v_mfma_f32_16x16x32_bf16 v[60:63], v[154:157], v[186:189], v[60:63]
	v_mfma_f32_16x16x32_bf16 v[56:59], v[162:165], v[186:189], v[56:59]
	v_mfma_f32_16x16x32_bf16 v[52:55], v[154:157], v[198:201], v[52:55]
	v_mfma_f32_16x16x32_bf16 v[48:51], v[162:165], v[198:201], v[48:51]
	v_mfma_f32_16x16x32_bf16 v[36:39], v[154:157], v[206:209], v[36:39]
	v_mfma_f32_16x16x32_bf16 v[32:35], v[162:165], v[206:209], v[32:35]
	v_mfma_f32_16x16x32_bf16 v[20:23], v[154:157], v[214:217], v[20:23]
	v_mfma_f32_16x16x32_bf16 v[16:19], v[162:165], v[214:217], v[16:19]
	v_mfma_f32_16x16x32_bf16 v[44:47], v[166:169], v[182:185], v[44:47]
	v_mfma_f32_16x16x32_bf16 v[40:43], v[174:177], v[182:185], v[40:43]
	v_mfma_f32_16x16x32_bf16 v[28:31], v[166:169], v[194:197], v[28:31]
	v_mfma_f32_16x16x32_bf16 v[24:27], v[174:177], v[194:197], v[24:27]
	v_mfma_f32_16x16x32_bf16 v[12:15], v[166:169], v[202:205], v[12:15]
	v_mfma_f32_16x16x32_bf16 v[8:11], v[174:177], v[202:205], v[8:11]
	v_mfma_f32_16x16x32_bf16 v[4:7], v[166:169], v[210:213], v[4:7]
	v_mfma_f32_16x16x32_bf16 v[0:3], v[174:177], v[210:213], v[0:3]
	v_mfma_f32_16x16x32_bf16 v[44:47], v[170:173], v[186:189], v[44:47]
	v_mfma_f32_16x16x32_bf16 v[40:43], v[178:181], v[186:189], v[40:43]
	v_mfma_f32_16x16x32_bf16 v[28:31], v[170:173], v[198:201], v[28:31]
	v_mfma_f32_16x16x32_bf16 v[24:27], v[178:181], v[198:201], v[24:27]
	v_mfma_f32_16x16x32_bf16 v[12:15], v[170:173], v[206:209], v[12:15]
	v_mfma_f32_16x16x32_bf16 v[8:11], v[178:181], v[206:209], v[8:11]
	v_mfma_f32_16x16x32_bf16 v[4:7], v[170:173], v[214:217], v[4:7]
	v_mfma_f32_16x16x32_bf16 v[0:3], v[178:181], v[214:217], v[0:3]
	s_barrier
	s_add_i32 s67, s67, 2
	s_add_u32 s36, s36, 0x100
	s_addc_u32 s37, s37, 0
	s_add_u32 s65, s65, 0x100
	s_addc_u32 s66, s66, 0
	s_cmp_gt_u32 s67, 13
	s_cbranch_scc1 .Lpeel_x2

.LBB0_884:
	s_ashr_i32 s17, s16, 31
	s_lshl_b64 s[18:19], s[16:17], 19
	s_add_u32 s18, s28, s18
	s_addc_u32 s19, s29, s19
	s_and_b64 s[24:25], s[42:43], exec
	s_cselect_b32 s17, s19, s31
	s_cselect_b32 s27, s18, s30
	s_ashr_i32 s13, s12, 31
	s_lshl_b64 s[24:25], s[12:13], 19
	s_add_u32 s24, s60, s24
	s_addc_u32 s25, s61, s25
	s_and_b64 s[36:37], s[42:43], exec
	s_cselect_b32 s13, s25, s35
	s_cselect_b32 s50, s24, s34
	s_add_u32 s30, s30, 0x40080
	s_addc_u32 s31, s31, 0
	s_add_u32 s51, s34, 0x100
	s_addc_u32 s52, s35, 0
	s_mov_b32 s53, -2
	s_waitcnt lgkmcnt(0)
	s_nop 0
	s_nop 0
	s_nop 0
	s_nop 0
	s_nop 0
	ds_read_b128 v[140:143], v149
	ds_read_b128 v[152:155], v149 offset:1024
	ds_read_b128 v[156:159], v149 offset:2048
	ds_read_b128 v[160:163], v149 offset:3072
	ds_read_b128 v[164:167], v150
	ds_read_b128 v[168:171], v150 offset:1024
	ds_read_b128 v[172:175], v150 offset:2048
	ds_read_b128 v[176:179], v150 offset:3072
	s_add_u32 s34, s30, 0xfffc0080
	s_addc_u32 s35, s31, -1
	s_cmp_eq_u32 s53, 12
	s_cselect_b32 s37, s17, s35
	s_cselect_b32 s36, s27, s34
	s_cselect_b32 s35, s13, s52
	s_cselect_b32 s34, s50, s51
	v_lshl_add_u64 v[214:215], s[30:31], 0, v[132:133]
	s_add_i32 m0, s15, 0xc000
	ds_read_b128 v[180:183], v151
	ds_read_b128 v[184:187], v151 offset:1024
	ds_read_b128 v[188:191], v151 offset:2048
	ds_read_b128 v[194:197], v151 offset:3072
	ds_read_b128 v[198:201], v151 offset:4096
	ds_read_b128 v[202:205], v151 offset:5120
	ds_read_b128 v[206:209], v151 offset:6144
	ds_read_b128 v[210:213], v151 offset:7168
	global_load_lds_dwordx4 v[214:215], off
	v_lshl_add_u64 v[214:215], s[30:31], 0, v[134:135]
	s_add_i32 m0, s15, 0xe000
	s_nop 0
	global_load_lds_dwordx4 v[214:215], off
	s_waitcnt vmcnt(8)
	s_waitcnt lgkmcnt(0)
	s_barrier
	s_waitcnt lgkmcnt(0)
	v_mfma_f32_16x16x32_bf16 v[124:127], v[140:143], v[180:183], 0
	v_mfma_f32_16x16x32_bf16 v[120:123], v[156:159], v[180:183], 0
	v_mfma_f32_16x16x32_bf16 v[108:111], v[140:143], v[188:191], 0
	v_mfma_f32_16x16x32_bf16 v[104:107], v[156:159], v[188:191], 0
	v_mfma_f32_16x16x32_bf16 v[92:95], v[140:143], v[198:201], 0
	v_mfma_f32_16x16x32_bf16 v[88:91], v[156:159], v[198:201], 0
	v_mfma_f32_16x16x32_bf16 v[76:79], v[140:143], v[206:209], 0
	v_mfma_f32_16x16x32_bf16 v[72:75], v[156:159], v[206:209], 0
	v_mfma_f32_16x16x32_bf16 v[124:127], v[152:155], v[184:187], v[124:127]
	v_mfma_f32_16x16x32_bf16 v[120:123], v[160:163], v[184:187], v[120:123]
	v_mfma_f32_16x16x32_bf16 v[108:111], v[152:155], v[194:197], v[108:111]
	v_mfma_f32_16x16x32_bf16 v[104:107], v[160:163], v[194:197], v[104:107]
	v_mfma_f32_16x16x32_bf16 v[92:95], v[152:155], v[202:205], v[92:95]
	v_mfma_f32_16x16x32_bf16 v[88:91], v[160:163], v[202:205], v[88:91]
	v_mfma_f32_16x16x32_bf16 v[76:79], v[152:155], v[210:213], v[76:79]
	v_mfma_f32_16x16x32_bf16 v[72:75], v[160:163], v[210:213], v[72:75]
	v_mfma_f32_16x16x32_bf16 v[116:119], v[164:167], v[180:183], 0
	v_mfma_f32_16x16x32_bf16 v[112:115], v[172:175], v[180:183], 0
	v_mfma_f32_16x16x32_bf16 v[100:103], v[164:167], v[188:191], 0
	v_mfma_f32_16x16x32_bf16 v[96:99], v[172:175], v[188:191], 0
	v_mfma_f32_16x16x32_bf16 v[84:87], v[164:167], v[198:201], 0
	v_mfma_f32_16x16x32_bf16 v[80:83], v[172:175], v[198:201], 0
	v_mfma_f32_16x16x32_bf16 v[68:71], v[164:167], v[206:209], 0
	v_mfma_f32_16x16x32_bf16 v[64:67], v[172:175], v[206:209], 0
	v_mfma_f32_16x16x32_bf16 v[116:119], v[168:171], v[184:187], v[116:119]
	v_mfma_f32_16x16x32_bf16 v[112:115], v[176:179], v[184:187], v[112:115]
	v_mfma_f32_16x16x32_bf16 v[100:103], v[168:171], v[194:197], v[100:103]
	v_mfma_f32_16x16x32_bf16 v[96:99], v[176:179], v[194:197], v[96:99]
	v_mfma_f32_16x16x32_bf16 v[84:87], v[168:171], v[202:205], v[84:87]
	v_mfma_f32_16x16x32_bf16 v[80:83], v[176:179], v[202:205], v[80:83]
	v_mfma_f32_16x16x32_bf16 v[68:71], v[168:171], v[210:213], v[68:71]
	v_mfma_f32_16x16x32_bf16 v[64:67], v[176:179], v[210:213], v[64:67]
	s_barrier
	s_add_i32 s54, s47, s14
	v_lshl_add_u64 v[214:215], s[34:35], 0, v[128:129]
	s_mov_b32 m0, s54
	ds_read_b128 v[180:183], v151 offset:16384
	ds_read_b128 v[184:187], v151 offset:17408
	ds_read_b128 v[188:191], v151 offset:18432
	ds_read_b128 v[194:197], v151 offset:19456
	ds_read_b128 v[198:201], v151 offset:20480
	ds_read_b128 v[202:205], v151 offset:21504
	ds_read_b128 v[206:209], v151 offset:22528
	ds_read_b128 v[210:213], v151 offset:23552
	global_load_lds_dwordx4 v[214:215], off
	s_add_i32 m0, s54, 0x2000
	s_add_u32 s54, s34, 0x40000
	v_lshl_add_u64 v[216:217], s[34:35], 0, v[130:131]
	s_addc_u32 s55, s35, 0
	s_add_i32 s56, s48, s14
	global_load_lds_dwordx4 v[216:217], off
	v_lshl_add_u64 v[218:219], s[54:55], 0, v[128:129]
	s_mov_b32 m0, s56
	v_lshl_add_u64 v[220:221], s[36:37], 0, v[130:131]
	global_load_lds_dwordx4 v[218:219], off
	v_lshl_add_u64 v[218:219], s[54:55], 0, v[130:131]
	s_add_i32 m0, s56, 0x2000
	s_nop 0
	global_load_lds_dwordx4 v[218:219], off
	v_lshl_add_u64 v[218:219], s[36:37], 0, v[128:129]
	s_mov_b32 m0, s15
	s_nop 0
	global_load_lds_dwordx4 v[218:219], off
	s_mov_b32 m0, s20
	s_nop 0
	global_load_lds_dwordx4 v[220:221], off
	s_waitcnt vmcnt(8)
	s_waitcnt lgkmcnt(0)
	s_barrier
	s_waitcnt lgkmcnt(0)
	v_mfma_f32_16x16x32_bf16 v[60:63], v[140:143], v[180:183], 0
	v_mfma_f32_16x16x32_bf16 v[56:59], v[156:159], v[180:183], 0
	v_mfma_f32_16x16x32_bf16 v[44:47], v[140:143], v[188:191], 0
	v_mfma_f32_16x16x32_bf16 v[40:43], v[156:159], v[188:191], 0
	v_mfma_f32_16x16x32_bf16 v[28:31], v[140:143], v[198:201], 0
	v_mfma_f32_16x16x32_bf16 v[24:27], v[156:159], v[198:201], 0
	v_mfma_f32_16x16x32_bf16 v[12:15], v[140:143], v[206:209], 0
	v_mfma_f32_16x16x32_bf16 v[8:11], v[156:159], v[206:209], 0
	v_mfma_f32_16x16x32_bf16 v[60:63], v[152:155], v[184:187], v[60:63]
	v_mfma_f32_16x16x32_bf16 v[56:59], v[160:163], v[184:187], v[56:59]
	v_mfma_f32_16x16x32_bf16 v[44:47], v[152:155], v[194:197], v[44:47]
	v_mfma_f32_16x16x32_bf16 v[40:43], v[160:163], v[194:197], v[40:43]
	v_mfma_f32_16x16x32_bf16 v[28:31], v[152:155], v[202:205], v[28:31]
	v_mfma_f32_16x16x32_bf16 v[24:27], v[160:163], v[202:205], v[24:27]
	v_mfma_f32_16x16x32_bf16 v[12:15], v[152:155], v[210:213], v[12:15]
	v_mfma_f32_16x16x32_bf16 v[8:11], v[160:163], v[210:213], v[8:11]
	v_mfma_f32_16x16x32_bf16 v[52:55], v[164:167], v[180:183], 0
	v_mfma_f32_16x16x32_bf16 v[48:51], v[172:175], v[180:183], 0
	v_mfma_f32_16x16x32_bf16 v[36:39], v[164:167], v[188:191], 0
	v_mfma_f32_16x16x32_bf16 v[32:35], v[172:175], v[188:191], 0
	v_mfma_f32_16x16x32_bf16 v[20:23], v[164:167], v[198:201], 0
	v_mfma_f32_16x16x32_bf16 v[16:19], v[172:175], v[198:201], 0
	v_mfma_f32_16x16x32_bf16 v[4:7], v[164:167], v[206:209], 0
	v_mfma_f32_16x16x32_bf16 v[0:3], v[172:175], v[206:209], 0
	v_mfma_f32_16x16x32_bf16 v[52:55], v[168:171], v[184:187], v[52:55]
	v_mfma_f32_16x16x32_bf16 v[48:51], v[176:179], v[184:187], v[48:51]
	v_mfma_f32_16x16x32_bf16 v[36:39], v[168:171], v[194:197], v[36:39]
	v_mfma_f32_16x16x32_bf16 v[32:35], v[176:179], v[194:197], v[32:35]
	v_mfma_f32_16x16x32_bf16 v[20:23], v[168:171], v[202:205], v[20:23]
	v_mfma_f32_16x16x32_bf16 v[16:19], v[176:179], v[202:205], v[16:19]
	v_mfma_f32_16x16x32_bf16 v[4:7], v[168:171], v[210:213], v[4:7]
	v_mfma_f32_16x16x32_bf16 v[0:3], v[176:179], v[210:213], v[0:3]
	s_barrier
	s_add_i32 s54, 0, 0x18000
	s_add_i32 s55, 0, 0x1c000
	v_add_u32_e32 v160, s54, v145
	v_add_u32_e32 v176, s55, v145
	ds_read_b128 v[140:143], v160
	ds_read_b128 v[152:155], v160 offset:1024
	ds_read_b128 v[156:159], v160 offset:2048
	ds_read_b128 v[160:163], v160 offset:3072
	ds_read_b128 v[164:167], v176
	ds_read_b128 v[168:171], v176 offset:1024
	ds_read_b128 v[172:175], v176 offset:2048
	ds_read_b128 v[176:179], v176 offset:3072
	s_add_u32 s36, s36, 0x40000
	s_addc_u32 s37, s37, 0
	s_mov_b32 m0, s21
	v_lshl_add_u64 v[222:223], s[36:37], 0, v[128:129]
	ds_read_b128 v[180:183], v151 offset:32768
	ds_read_b128 v[184:187], v151 offset:33792
	ds_read_b128 v[188:191], v151 offset:34816
	ds_read_b128 v[194:197], v151 offset:35840
	ds_read_b128 v[198:201], v151 offset:36864
	ds_read_b128 v[202:205], v151 offset:37888
	ds_read_b128 v[206:209], v151 offset:38912
	ds_read_b128 v[210:213], v151 offset:39936
	global_load_lds_dwordx4 v[222:223], off
	v_lshl_add_u64 v[222:223], s[36:37], 0, v[130:131]
	s_mov_b32 m0, s33
	s_nop 0
	global_load_lds_dwordx4 v[222:223], off
	s_waitcnt vmcnt(8)
	s_waitcnt lgkmcnt(0)
	s_barrier
	s_waitcnt lgkmcnt(0)
	v_mfma_f32_16x16x32_bf16 v[124:127], v[140:143], v[180:183], v[124:127]
	v_mfma_f32_16x16x32_bf16 v[120:123], v[156:159], v[180:183], v[120:123]
	v_mfma_f32_16x16x32_bf16 v[108:111], v[140:143], v[188:191], v[108:111]
	v_mfma_f32_16x16x32_bf16 v[104:107], v[156:159], v[188:191], v[104:107]
	v_mfma_f32_16x16x32_bf16 v[92:95], v[140:143], v[198:201], v[92:95]
	v_mfma_f32_16x16x32_bf16 v[88:91], v[156:159], v[198:201], v[88:91]
	v_mfma_f32_16x16x32_bf16 v[76:79], v[140:143], v[206:209], v[76:79]
	v_mfma_f32_16x16x32_bf16 v[72:75], v[156:159], v[206:209], v[72:75]
	v_mfma_f32_16x16x32_bf16 v[124:127], v[152:155], v[184:187], v[124:127]
	v_mfma_f32_16x16x32_bf16 v[120:123], v[160:163], v[184:187], v[120:123]
	v_mfma_f32_16x16x32_bf16 v[108:111], v[152:155], v[194:197], v[108:111]
	v_mfma_f32_16x16x32_bf16 v[104:107], v[160:163], v[194:197], v[104:107]
	v_mfma_f32_16x16x32_bf16 v[92:95], v[152:155], v[202:205], v[92:95]
	v_mfma_f32_16x16x32_bf16 v[88:91], v[160:163], v[202:205], v[88:91]
	v_mfma_f32_16x16x32_bf16 v[76:79], v[152:155], v[210:213], v[76:79]
	v_mfma_f32_16x16x32_bf16 v[72:75], v[160:163], v[210:213], v[72:75]
	v_mfma_f32_16x16x32_bf16 v[116:119], v[164:167], v[180:183], v[116:119]
	v_mfma_f32_16x16x32_bf16 v[112:115], v[172:175], v[180:183], v[112:115]
	v_mfma_f32_16x16x32_bf16 v[100:103], v[164:167], v[188:191], v[100:103]
	v_mfma_f32_16x16x32_bf16 v[96:99], v[172:175], v[188:191], v[96:99]
	v_mfma_f32_16x16x32_bf16 v[84:87], v[164:167], v[198:201], v[84:87]
	v_mfma_f32_16x16x32_bf16 v[80:83], v[172:175], v[198:201], v[80:83]
	v_mfma_f32_16x16x32_bf16 v[68:71], v[164:167], v[206:209], v[68:71]
	v_mfma_f32_16x16x32_bf16 v[64:67], v[172:175], v[206:209], v[64:67]
	v_mfma_f32_16x16x32_bf16 v[116:119], v[168:171], v[184:187], v[116:119]
	v_mfma_f32_16x16x32_bf16 v[112:115], v[176:179], v[184:187], v[112:115]
	v_mfma_f32_16x16x32_bf16 v[100:103], v[168:171], v[194:197], v[100:103]
	v_mfma_f32_16x16x32_bf16 v[96:99], v[176:179], v[194:197], v[96:99]
	v_mfma_f32_16x16x32_bf16 v[84:87], v[168:171], v[202:205], v[84:87]
	v_mfma_f32_16x16x32_bf16 v[80:83], v[176:179], v[202:205], v[80:83]
	v_mfma_f32_16x16x32_bf16 v[68:71], v[168:171], v[210:213], v[68:71]
	v_mfma_f32_16x16x32_bf16 v[64:67], v[176:179], v[210:213], v[64:67]
	s_barrier
	s_add_i32 s36, s54, s14
	v_lshl_add_u64 v[214:215], v[214:215], 0, s[8:9]
	s_mov_b32 m0, s36
	ds_read_b128 v[180:183], v151 offset:49152
	ds_read_b128 v[184:187], v151 offset:50176
	ds_read_b128 v[188:191], v151 offset:51200
	ds_read_b128 v[194:197], v151 offset:52224
	ds_read_b128 v[198:201], v151 offset:53248
	ds_read_b128 v[202:205], v151 offset:54272
	ds_read_b128 v[206:209], v151 offset:55296
	ds_read_b128 v[210:213], v151 offset:56320
	global_load_lds_dwordx4 v[214:215], off
	s_add_i32 m0, s36, 0x2000
	s_add_u32 s34, s34, 0x40080
	v_lshl_add_u64 v[214:215], v[216:217], 0, s[8:9]
	s_addc_u32 s35, s35, 0
	s_add_i32 s36, s55, s14
	global_load_lds_dwordx4 v[214:215], off
	v_lshl_add_u64 v[214:215], s[34:35], 0, v[128:129]
	s_mov_b32 m0, s36
	s_nop 0
	global_load_lds_dwordx4 v[214:215], off
	v_lshl_add_u64 v[214:215], s[34:35], 0, v[130:131]
	s_add_i32 m0, s36, 0x2000
	s_nop 0
	global_load_lds_dwordx4 v[214:215], off
	v_lshl_add_u64 v[214:215], v[218:219], 0, s[8:9]
	s_mov_b32 m0, s45
	s_nop 0
	global_load_lds_dwordx4 v[214:215], off
	v_lshl_add_u64 v[214:215], v[220:221], 0, s[8:9]
	s_mov_b32 m0, s46
	s_nop 0
	global_load_lds_dwordx4 v[214:215], off
	s_waitcnt vmcnt(8)
	s_waitcnt lgkmcnt(0)
	s_barrier
	s_waitcnt lgkmcnt(0)
	v_mfma_f32_16x16x32_bf16 v[60:63], v[140:143], v[180:183], v[60:63]
	v_mfma_f32_16x16x32_bf16 v[56:59], v[156:159], v[180:183], v[56:59]
	v_mfma_f32_16x16x32_bf16 v[44:47], v[140:143], v[188:191], v[44:47]
	v_mfma_f32_16x16x32_bf16 v[40:43], v[156:159], v[188:191], v[40:43]
	v_mfma_f32_16x16x32_bf16 v[28:31], v[140:143], v[198:201], v[28:31]
	v_mfma_f32_16x16x32_bf16 v[24:27], v[156:159], v[198:201], v[24:27]
	v_mfma_f32_16x16x32_bf16 v[12:15], v[140:143], v[206:209], v[12:15]
	v_mfma_f32_16x16x32_bf16 v[8:11], v[156:159], v[206:209], v[8:11]
	v_mfma_f32_16x16x32_bf16 v[60:63], v[152:155], v[184:187], v[60:63]
	v_mfma_f32_16x16x32_bf16 v[56:59], v[160:163], v[184:187], v[56:59]
	v_mfma_f32_16x16x32_bf16 v[44:47], v[152:155], v[194:197], v[44:47]
	v_mfma_f32_16x16x32_bf16 v[40:43], v[160:163], v[194:197], v[40:43]
	v_mfma_f32_16x16x32_bf16 v[28:31], v[152:155], v[202:205], v[28:31]
	v_mfma_f32_16x16x32_bf16 v[24:27], v[160:163], v[202:205], v[24:27]
	v_mfma_f32_16x16x32_bf16 v[12:15], v[152:155], v[210:213], v[12:15]
	v_mfma_f32_16x16x32_bf16 v[8:11], v[160:163], v[210:213], v[8:11]
	v_mfma_f32_16x16x32_bf16 v[52:55], v[164:167], v[180:183], v[52:55]
	v_mfma_f32_16x16x32_bf16 v[48:51], v[172:175], v[180:183], v[48:51]
	v_mfma_f32_16x16x32_bf16 v[36:39], v[164:167], v[188:191], v[36:39]
	v_mfma_f32_16x16x32_bf16 v[32:35], v[172:175], v[188:191], v[32:35]
	v_mfma_f32_16x16x32_bf16 v[20:23], v[164:167], v[198:201], v[20:23]
	v_mfma_f32_16x16x32_bf16 v[16:19], v[172:175], v[198:201], v[16:19]
	v_mfma_f32_16x16x32_bf16 v[4:7], v[164:167], v[206:209], v[4:7]
	v_mfma_f32_16x16x32_bf16 v[0:3], v[172:175], v[206:209], v[0:3]
	v_mfma_f32_16x16x32_bf16 v[52:55], v[168:171], v[184:187], v[52:55]
	v_mfma_f32_16x16x32_bf16 v[48:51], v[176:179], v[184:187], v[48:51]
	v_mfma_f32_16x16x32_bf16 v[36:39], v[168:171], v[194:197], v[36:39]
	v_mfma_f32_16x16x32_bf16 v[32:35], v[176:179], v[194:197], v[32:35]
	v_mfma_f32_16x16x32_bf16 v[20:23], v[168:171], v[202:205], v[20:23]
	v_mfma_f32_16x16x32_bf16 v[16:19], v[176:179], v[202:205], v[16:19]
	v_mfma_f32_16x16x32_bf16 v[4:7], v[168:171], v[210:213], v[4:7]
	v_mfma_f32_16x16x32_bf16 v[0:3], v[176:179], v[210:213], v[0:3]
	s_barrier
	s_add_i32 s53, s53, 2
	s_add_u32 s30, s30, 0x100
	s_addc_u32 s31, s31, 0
	s_add_u32 s51, s51, 0x100
	s_addc_u32 s52, s52, 0
	s_cmp_gt_u32 s53, 13
	s_cbranch_scc1 .Lpeel_x3

.LBB0_973:
	s_ashr_i32 s17, s16, 31
	s_lshl_b64 s[18:19], s[16:17], 19
	s_add_u32 s18, s82, s18
	s_addc_u32 s19, s83, s19
	s_and_b64 s[20:21], s[40:41], exec
	s_cselect_b32 s17, s19, s27
	s_cselect_b32 s47, s18, s26
	s_ashr_i32 s13, s12, 31
	s_lshl_b64 s[20:21], s[12:13], 19
	s_add_u32 s20, s58, s20
	s_addc_u32 s21, s59, s21
	s_and_b64 s[30:31], s[40:41], exec
	s_cselect_b32 s13, s21, s29
	s_cselect_b32 s48, s20, s28
	s_add_u32 s26, s26, 0x40080
	s_addc_u32 s27, s27, 0
	s_add_u32 s49, s28, 0x100
	s_addc_u32 s50, s29, 0
	s_mov_b32 s51, -2
	s_nop 0
	s_nop 0
	s_nop 0
	s_nop 0
	s_nop 0
	ds_read_b128 v[154:157], v150
	ds_read_b128 v[158:161], v150 offset:1024
	ds_read_b128 v[162:165], v150 offset:2048
	ds_read_b128 v[166:169], v150 offset:3072
	ds_read_b128 v[170:173], v151
	ds_read_b128 v[174:177], v151 offset:1024
	ds_read_b128 v[178:181], v151 offset:2048
	ds_read_b128 v[182:185], v151 offset:3072
	s_add_u32 s28, s26, 0xfffc0080
	s_addc_u32 s29, s27, -1
	s_cmp_eq_u32 s51, 12
	s_cselect_b32 s31, s17, s29
	s_cselect_b32 s30, s47, s28
	s_cselect_b32 s29, s13, s50
	s_cselect_b32 s28, s48, s49
	v_lshl_add_u64 v[146:147], s[26:27], 0, v[138:139]
	s_add_i32 m0, s33, 0xc000
	ds_read_b128 v[186:189], v152
	ds_read_b128 v[194:197], v152 offset:1024
	ds_read_b128 v[198:201], v152 offset:2048
	ds_read_b128 v[202:205], v152 offset:3072
	ds_read_b128 v[206:209], v152 offset:4096
	ds_read_b128 v[210:213], v152 offset:5120
	ds_read_b128 v[214:217], v152 offset:6144
	ds_read_b128 v[218:221], v152 offset:7168
	global_load_lds_dwordx4 v[146:147], off
	v_lshl_add_u64 v[146:147], s[26:27], 0, v[140:141]
	s_add_i32 m0, s33, 0xe000
	s_nop 0
	global_load_lds_dwordx4 v[146:147], off
	s_waitcnt vmcnt(8)
	s_waitcnt lgkmcnt(0)
	s_barrier
	s_waitcnt lgkmcnt(0)
	v_mfma_f32_16x16x32_bf16 v[124:127], v[154:157], v[186:189], 0
	v_mfma_f32_16x16x32_bf16 v[120:123], v[162:165], v[186:189], 0
	v_mfma_f32_16x16x32_bf16 v[108:111], v[154:157], v[198:201], 0
	v_mfma_f32_16x16x32_bf16 v[104:107], v[162:165], v[198:201], 0
	v_mfma_f32_16x16x32_bf16 v[92:95], v[154:157], v[206:209], 0
	v_mfma_f32_16x16x32_bf16 v[88:91], v[162:165], v[206:209], 0
	v_mfma_f32_16x16x32_bf16 v[76:79], v[154:157], v[214:217], 0
	v_mfma_f32_16x16x32_bf16 v[72:75], v[162:165], v[214:217], 0
	v_mfma_f32_16x16x32_bf16 v[124:127], v[158:161], v[194:197], v[124:127]
	v_mfma_f32_16x16x32_bf16 v[120:123], v[166:169], v[194:197], v[120:123]
	v_mfma_f32_16x16x32_bf16 v[108:111], v[158:161], v[202:205], v[108:111]
	v_mfma_f32_16x16x32_bf16 v[104:107], v[166:169], v[202:205], v[104:107]
	v_mfma_f32_16x16x32_bf16 v[92:95], v[158:161], v[210:213], v[92:95]
	v_mfma_f32_16x16x32_bf16 v[88:91], v[166:169], v[210:213], v[88:91]
	v_mfma_f32_16x16x32_bf16 v[76:79], v[158:161], v[218:221], v[76:79]
	v_mfma_f32_16x16x32_bf16 v[72:75], v[166:169], v[218:221], v[72:75]
	v_mfma_f32_16x16x32_bf16 v[116:119], v[170:173], v[186:189], 0
	v_mfma_f32_16x16x32_bf16 v[112:115], v[178:181], v[186:189], 0
	v_mfma_f32_16x16x32_bf16 v[100:103], v[170:173], v[198:201], 0
	v_mfma_f32_16x16x32_bf16 v[96:99], v[178:181], v[198:201], 0
	v_mfma_f32_16x16x32_bf16 v[84:87], v[170:173], v[206:209], 0
	v_mfma_f32_16x16x32_bf16 v[80:83], v[178:181], v[206:209], 0
	v_mfma_f32_16x16x32_bf16 v[68:71], v[170:173], v[214:217], 0
	v_mfma_f32_16x16x32_bf16 v[64:67], v[178:181], v[214:217], 0
	v_mfma_f32_16x16x32_bf16 v[116:119], v[174:177], v[194:197], v[116:119]
	v_mfma_f32_16x16x32_bf16 v[112:115], v[182:185], v[194:197], v[112:115]
	v_mfma_f32_16x16x32_bf16 v[100:103], v[174:177], v[202:205], v[100:103]
	v_mfma_f32_16x16x32_bf16 v[96:99], v[182:185], v[202:205], v[96:99]
	v_mfma_f32_16x16x32_bf16 v[84:87], v[174:177], v[210:213], v[84:87]
	v_mfma_f32_16x16x32_bf16 v[80:83], v[182:185], v[210:213], v[80:83]
	v_mfma_f32_16x16x32_bf16 v[68:71], v[174:177], v[218:221], v[68:71]
	v_mfma_f32_16x16x32_bf16 v[64:67], v[182:185], v[218:221], v[64:67]
	s_barrier
	s_add_i32 s52, s43, s14
	v_lshl_add_u64 v[146:147], s[28:29], 0, v[132:133]
	s_mov_b32 m0, s52
	ds_read_b128 v[186:189], v152 offset:16384
	ds_read_b128 v[194:197], v152 offset:17408
	ds_read_b128 v[198:201], v152 offset:18432
	ds_read_b128 v[202:205], v152 offset:19456
	ds_read_b128 v[206:209], v152 offset:20480
	ds_read_b128 v[210:213], v152 offset:21504
	ds_read_b128 v[214:217], v152 offset:22528
	ds_read_b128 v[218:221], v152 offset:23552
	global_load_lds_dwordx4 v[146:147], off
	s_add_i32 m0, s52, 0x2000
	s_add_u32 s52, s28, 0x40000
	v_lshl_add_u64 v[190:191], s[28:29], 0, v[128:129]
	s_addc_u32 s53, s29, 0
	s_add_i32 s54, s44, s14
	global_load_lds_dwordx4 v[190:191], off
	v_lshl_add_u64 v[222:223], s[52:53], 0, v[132:133]
	s_mov_b32 m0, s54
	v_lshl_add_u64 v[224:225], s[30:31], 0, v[130:131]
	global_load_lds_dwordx4 v[222:223], off
	v_lshl_add_u64 v[222:223], s[52:53], 0, v[128:129]
	s_add_i32 m0, s54, 0x2000
	s_nop 0
	global_load_lds_dwordx4 v[222:223], off
	v_lshl_add_u64 v[222:223], s[30:31], 0, v[134:135]
	s_mov_b32 m0, s33
	s_nop 0
	global_load_lds_dwordx4 v[222:223], off
	s_mov_b32 m0, s34
	s_nop 0
	global_load_lds_dwordx4 v[224:225], off
	s_waitcnt vmcnt(8)
	s_waitcnt lgkmcnt(0)
	s_barrier
	s_waitcnt lgkmcnt(0)
	v_mfma_f32_16x16x32_bf16 v[60:63], v[154:157], v[186:189], 0
	v_mfma_f32_16x16x32_bf16 v[56:59], v[162:165], v[186:189], 0
	v_mfma_f32_16x16x32_bf16 v[44:47], v[154:157], v[198:201], 0
	v_mfma_f32_16x16x32_bf16 v[40:43], v[162:165], v[198:201], 0
	v_mfma_f32_16x16x32_bf16 v[28:31], v[154:157], v[206:209], 0
	v_mfma_f32_16x16x32_bf16 v[24:27], v[162:165], v[206:209], 0
	v_mfma_f32_16x16x32_bf16 v[12:15], v[154:157], v[214:217], 0
	v_mfma_f32_16x16x32_bf16 v[8:11], v[162:165], v[214:217], 0
	v_mfma_f32_16x16x32_bf16 v[60:63], v[158:161], v[194:197], v[60:63]
	v_mfma_f32_16x16x32_bf16 v[56:59], v[166:169], v[194:197], v[56:59]
	v_mfma_f32_16x16x32_bf16 v[44:47], v[158:161], v[202:205], v[44:47]
	v_mfma_f32_16x16x32_bf16 v[40:43], v[166:169], v[202:205], v[40:43]
	v_mfma_f32_16x16x32_bf16 v[28:31], v[158:161], v[210:213], v[28:31]
	v_mfma_f32_16x16x32_bf16 v[24:27], v[166:169], v[210:213], v[24:27]
	v_mfma_f32_16x16x32_bf16 v[12:15], v[158:161], v[218:221], v[12:15]
	v_mfma_f32_16x16x32_bf16 v[8:11], v[166:169], v[218:221], v[8:11]
	v_mfma_f32_16x16x32_bf16 v[52:55], v[170:173], v[186:189], 0
	v_mfma_f32_16x16x32_bf16 v[48:51], v[178:181], v[186:189], 0
	v_mfma_f32_16x16x32_bf16 v[36:39], v[170:173], v[198:201], 0
	v_mfma_f32_16x16x32_bf16 v[32:35], v[178:181], v[198:201], 0
	v_mfma_f32_16x16x32_bf16 v[20:23], v[170:173], v[206:209], 0
	v_mfma_f32_16x16x32_bf16 v[16:19], v[178:181], v[206:209], 0
	v_mfma_f32_16x16x32_bf16 v[4:7], v[170:173], v[214:217], 0
	v_mfma_f32_16x16x32_bf16 v[0:3], v[178:181], v[214:217], 0
	v_mfma_f32_16x16x32_bf16 v[52:55], v[174:177], v[194:197], v[52:55]
	v_mfma_f32_16x16x32_bf16 v[48:51], v[182:185], v[194:197], v[48:51]
	v_mfma_f32_16x16x32_bf16 v[36:39], v[174:177], v[202:205], v[36:39]
	v_mfma_f32_16x16x32_bf16 v[32:35], v[182:185], v[202:205], v[32:35]
	v_mfma_f32_16x16x32_bf16 v[20:23], v[174:177], v[210:213], v[20:23]
	v_mfma_f32_16x16x32_bf16 v[16:19], v[182:185], v[210:213], v[16:19]
	v_mfma_f32_16x16x32_bf16 v[4:7], v[174:177], v[218:221], v[4:7]
	v_mfma_f32_16x16x32_bf16 v[0:3], v[182:185], v[218:221], v[0:3]
	s_barrier
	s_add_i32 s52, 0, 0x18000
	s_add_i32 s53, 0, 0x1c000
	v_add_u32_e32 v166, s52, v149
	v_add_u32_e32 v182, s53, v149
	ds_read_b128 v[154:157], v166
	ds_read_b128 v[158:161], v166 offset:1024
	ds_read_b128 v[162:165], v166 offset:2048
	ds_read_b128 v[166:169], v166 offset:3072
	ds_read_b128 v[170:173], v182
	ds_read_b128 v[174:177], v182 offset:1024
	ds_read_b128 v[178:181], v182 offset:2048
	ds_read_b128 v[182:185], v182 offset:3072
	s_add_u32 s30, s30, 0x40000
	s_addc_u32 s31, s31, 0
	s_mov_b32 m0, s35
	v_lshl_add_u64 v[226:227], s[30:31], 0, v[134:135]
	ds_read_b128 v[186:189], v152 offset:32768
	ds_read_b128 v[194:197], v152 offset:33792
	ds_read_b128 v[198:201], v152 offset:34816
	ds_read_b128 v[202:205], v152 offset:35840
	ds_read_b128 v[206:209], v152 offset:36864
	ds_read_b128 v[210:213], v152 offset:37888
	ds_read_b128 v[214:217], v152 offset:38912
	ds_read_b128 v[218:221], v152 offset:39936
	global_load_lds_dwordx4 v[226:227], off
	v_lshl_add_u64 v[226:227], s[30:31], 0, v[130:131]
	s_mov_b32 m0, s36
	s_nop 0
	global_load_lds_dwordx4 v[226:227], off
	s_waitcnt vmcnt(8)
	s_waitcnt lgkmcnt(0)
	s_barrier
	s_waitcnt lgkmcnt(0)
	v_mfma_f32_16x16x32_bf16 v[124:127], v[154:157], v[186:189], v[124:127]
	v_mfma_f32_16x16x32_bf16 v[120:123], v[162:165], v[186:189], v[120:123]
	v_mfma_f32_16x16x32_bf16 v[108:111], v[154:157], v[198:201], v[108:111]
	v_mfma_f32_16x16x32_bf16 v[104:107], v[162:165], v[198:201], v[104:107]
	v_mfma_f32_16x16x32_bf16 v[92:95], v[154:157], v[206:209], v[92:95]
	v_mfma_f32_16x16x32_bf16 v[88:91], v[162:165], v[206:209], v[88:91]
	v_mfma_f32_16x16x32_bf16 v[76:79], v[154:157], v[214:217], v[76:79]
	v_mfma_f32_16x16x32_bf16 v[72:75], v[162:165], v[214:217], v[72:75]
	v_mfma_f32_16x16x32_bf16 v[124:127], v[158:161], v[194:197], v[124:127]
	v_mfma_f32_16x16x32_bf16 v[120:123], v[166:169], v[194:197], v[120:123]
	v_mfma_f32_16x16x32_bf16 v[108:111], v[158:161], v[202:205], v[108:111]
	v_mfma_f32_16x16x32_bf16 v[104:107], v[166:169], v[202:205], v[104:107]
	v_mfma_f32_16x16x32_bf16 v[92:95], v[158:161], v[210:213], v[92:95]
	v_mfma_f32_16x16x32_bf16 v[88:91], v[166:169], v[210:213], v[88:91]
	v_mfma_f32_16x16x32_bf16 v[76:79], v[158:161], v[218:221], v[76:79]
	v_mfma_f32_16x16x32_bf16 v[72:75], v[166:169], v[218:221], v[72:75]
	v_mfma_f32_16x16x32_bf16 v[116:119], v[170:173], v[186:189], v[116:119]
	v_mfma_f32_16x16x32_bf16 v[112:115], v[178:181], v[186:189], v[112:115]
	v_mfma_f32_16x16x32_bf16 v[100:103], v[170:173], v[198:201], v[100:103]
	v_mfma_f32_16x16x32_bf16 v[96:99], v[178:181], v[198:201], v[96:99]
	v_mfma_f32_16x16x32_bf16 v[84:87], v[170:173], v[206:209], v[84:87]
	v_mfma_f32_16x16x32_bf16 v[80:83], v[178:181], v[206:209], v[80:83]
	v_mfma_f32_16x16x32_bf16 v[68:71], v[170:173], v[214:217], v[68:71]
	v_mfma_f32_16x16x32_bf16 v[64:67], v[178:181], v[214:217], v[64:67]
	v_mfma_f32_16x16x32_bf16 v[116:119], v[174:177], v[194:197], v[116:119]
	v_mfma_f32_16x16x32_bf16 v[112:115], v[182:185], v[194:197], v[112:115]
	v_mfma_f32_16x16x32_bf16 v[100:103], v[174:177], v[202:205], v[100:103]
	v_mfma_f32_16x16x32_bf16 v[96:99], v[182:185], v[202:205], v[96:99]
	v_mfma_f32_16x16x32_bf16 v[84:87], v[174:177], v[210:213], v[84:87]
	v_mfma_f32_16x16x32_bf16 v[80:83], v[182:185], v[210:213], v[80:83]
	v_mfma_f32_16x16x32_bf16 v[68:71], v[174:177], v[218:221], v[68:71]
	v_mfma_f32_16x16x32_bf16 v[64:67], v[182:185], v[218:221], v[64:67]
	s_barrier
	s_add_i32 s30, s52, s14
	v_lshl_add_u64 v[146:147], v[146:147], 0, s[6:7]
	s_mov_b32 m0, s30
	ds_read_b128 v[186:189], v152 offset:49152
	ds_read_b128 v[194:197], v152 offset:50176
	ds_read_b128 v[198:201], v152 offset:51200
	ds_read_b128 v[202:205], v152 offset:52224
	ds_read_b128 v[206:209], v152 offset:53248
	ds_read_b128 v[210:213], v152 offset:54272
	ds_read_b128 v[214:217], v152 offset:55296
	ds_read_b128 v[218:221], v152 offset:56320
	global_load_lds_dwordx4 v[146:147], off
	s_add_i32 m0, s30, 0x2000
	s_add_u32 s28, s28, 0x40080
	v_lshl_add_u64 v[146:147], v[190:191], 0, s[6:7]
	s_addc_u32 s29, s29, 0
	s_add_i32 s30, s53, s14
	global_load_lds_dwordx4 v[146:147], off
	v_lshl_add_u64 v[146:147], s[28:29], 0, v[132:133]
	s_mov_b32 m0, s30
	s_nop 0
	global_load_lds_dwordx4 v[146:147], off
	v_lshl_add_u64 v[146:147], s[28:29], 0, v[128:129]
	s_add_i32 m0, s30, 0x2000
	s_nop 0
	global_load_lds_dwordx4 v[146:147], off
	v_lshl_add_u64 v[146:147], v[222:223], 0, s[6:7]
	s_mov_b32 m0, s37
	s_nop 0
	global_load_lds_dwordx4 v[146:147], off
	v_lshl_add_u64 v[146:147], v[224:225], 0, s[6:7]
	s_mov_b32 m0, s42
	s_nop 0
	global_load_lds_dwordx4 v[146:147], off
	s_waitcnt vmcnt(8)
	s_waitcnt lgkmcnt(0)
	s_barrier
	s_waitcnt lgkmcnt(0)
	v_mfma_f32_16x16x32_bf16 v[60:63], v[154:157], v[186:189], v[60:63]
	v_mfma_f32_16x16x32_bf16 v[56:59], v[162:165], v[186:189], v[56:59]
	v_mfma_f32_16x16x32_bf16 v[44:47], v[154:157], v[198:201], v[44:47]
	v_mfma_f32_16x16x32_bf16 v[40:43], v[162:165], v[198:201], v[40:43]
	v_mfma_f32_16x16x32_bf16 v[28:31], v[154:157], v[206:209], v[28:31]
	v_mfma_f32_16x16x32_bf16 v[24:27], v[162:165], v[206:209], v[24:27]
	v_mfma_f32_16x16x32_bf16 v[12:15], v[154:157], v[214:217], v[12:15]
	v_mfma_f32_16x16x32_bf16 v[8:11], v[162:165], v[214:217], v[8:11]
	v_mfma_f32_16x16x32_bf16 v[60:63], v[158:161], v[194:197], v[60:63]
	v_mfma_f32_16x16x32_bf16 v[56:59], v[166:169], v[194:197], v[56:59]
	v_mfma_f32_16x16x32_bf16 v[44:47], v[158:161], v[202:205], v[44:47]
	v_mfma_f32_16x16x32_bf16 v[40:43], v[166:169], v[202:205], v[40:43]
	v_mfma_f32_16x16x32_bf16 v[28:31], v[158:161], v[210:213], v[28:31]
	v_mfma_f32_16x16x32_bf16 v[24:27], v[166:169], v[210:213], v[24:27]
	v_mfma_f32_16x16x32_bf16 v[12:15], v[158:161], v[218:221], v[12:15]
	v_mfma_f32_16x16x32_bf16 v[8:11], v[166:169], v[218:221], v[8:11]
	v_mfma_f32_16x16x32_bf16 v[52:55], v[170:173], v[186:189], v[52:55]
	v_mfma_f32_16x16x32_bf16 v[48:51], v[178:181], v[186:189], v[48:51]
	v_mfma_f32_16x16x32_bf16 v[36:39], v[170:173], v[198:201], v[36:39]
	v_mfma_f32_16x16x32_bf16 v[32:35], v[178:181], v[198:201], v[32:35]
	v_mfma_f32_16x16x32_bf16 v[20:23], v[170:173], v[206:209], v[20:23]
	v_mfma_f32_16x16x32_bf16 v[16:19], v[178:181], v[206:209], v[16:19]
	v_mfma_f32_16x16x32_bf16 v[4:7], v[170:173], v[214:217], v[4:7]
	v_mfma_f32_16x16x32_bf16 v[0:3], v[178:181], v[214:217], v[0:3]
	v_mfma_f32_16x16x32_bf16 v[52:55], v[174:177], v[194:197], v[52:55]
	v_mfma_f32_16x16x32_bf16 v[48:51], v[182:185], v[194:197], v[48:51]
	v_mfma_f32_16x16x32_bf16 v[36:39], v[174:177], v[202:205], v[36:39]
	v_mfma_f32_16x16x32_bf16 v[32:35], v[182:185], v[202:205], v[32:35]
	v_mfma_f32_16x16x32_bf16 v[20:23], v[174:177], v[210:213], v[20:23]
	v_mfma_f32_16x16x32_bf16 v[16:19], v[182:185], v[210:213], v[16:19]
	v_mfma_f32_16x16x32_bf16 v[4:7], v[174:177], v[218:221], v[4:7]
	v_mfma_f32_16x16x32_bf16 v[0:3], v[182:185], v[218:221], v[0:3]
	s_barrier
	s_add_i32 s51, s51, 2
	s_add_u32 s26, s26, 0x100
	s_addc_u32 s27, s27, 0
	s_add_u32 s49, s49, 0x100
	s_addc_u32 s50, s50, 0
	s_cmp_gt_u32 s51, 13
	s_cbranch_scc1 .Lpeel_x4

.LBB0_1054:
	s_add_u32 s37, s16, 0x100
	s_addc_u32 s38, s17, 0
	s_mov_b32 s39, -2
	s_nop 0
	s_nop 0
	s_nop 0
	s_nop 0
	s_nop 0
	ds_read_b128 v[142:145], v147
	ds_read_b128 v[150:153], v147 offset:1024
	ds_read_b128 v[154:157], v147 offset:2048
	ds_read_b128 v[158:161], v147 offset:3072
	ds_read_b128 v[162:165], v148
	ds_read_b128 v[166:169], v148 offset:1024
	ds_read_b128 v[170:173], v148 offset:2048
	ds_read_b128 v[174:177], v148 offset:3072
	s_add_u32 s16, s14, 0x100
	s_addc_u32 s17, s15, 0
	s_cmp_eq_u32 s39, 40
	s_cselect_b32 s21, s5, s17
	s_cselect_b32 s20, s4, s16
	s_cselect_b32 s19, s13, s38
	s_cselect_b32 s18, s12, s37
	v_lshl_add_u64 v[210:211], s[14:15], 0, v[134:135]
	s_add_i32 m0, s23, 0xc000
	ds_read_b128 v[178:181], v149
	ds_read_b128 v[182:185], v149 offset:1024
	ds_read_b128 v[186:189], v149 offset:2048
	ds_read_b128 v[190:193], v149 offset:3072
	ds_read_b128 v[194:197], v149 offset:4096
	ds_read_b128 v[198:201], v149 offset:5120
	ds_read_b128 v[202:205], v149 offset:6144
	ds_read_b128 v[206:209], v149 offset:7168
	global_load_lds_dwordx4 v[210:211], off
	v_lshl_add_u64 v[210:211], s[14:15], 0, v[136:137]
	s_add_i32 m0, s23, 0xe000
	s_nop 0
	global_load_lds_dwordx4 v[210:211], off
	s_waitcnt vmcnt(8)
	s_waitcnt lgkmcnt(0)
	s_barrier
	s_waitcnt lgkmcnt(0)
	v_mfma_f32_16x16x32_bf16 v[124:127], v[142:145], v[178:181], 0
	v_mfma_f32_16x16x32_bf16 v[120:123], v[154:157], v[178:181], 0
	v_mfma_f32_16x16x32_bf16 v[108:111], v[142:145], v[186:189], 0
	v_mfma_f32_16x16x32_bf16 v[104:107], v[154:157], v[186:189], 0
	v_mfma_f32_16x16x32_bf16 v[92:95], v[142:145], v[194:197], 0
	v_mfma_f32_16x16x32_bf16 v[88:91], v[154:157], v[194:197], 0
	v_mfma_f32_16x16x32_bf16 v[76:79], v[142:145], v[202:205], 0
	v_mfma_f32_16x16x32_bf16 v[72:75], v[154:157], v[202:205], 0
	v_mfma_f32_16x16x32_bf16 v[124:127], v[150:153], v[182:185], v[124:127]
	v_mfma_f32_16x16x32_bf16 v[120:123], v[158:161], v[182:185], v[120:123]
	v_mfma_f32_16x16x32_bf16 v[108:111], v[150:153], v[190:193], v[108:111]
	v_mfma_f32_16x16x32_bf16 v[104:107], v[158:161], v[190:193], v[104:107]
	v_mfma_f32_16x16x32_bf16 v[92:95], v[150:153], v[198:201], v[92:95]
	v_mfma_f32_16x16x32_bf16 v[88:91], v[158:161], v[198:201], v[88:91]
	v_mfma_f32_16x16x32_bf16 v[76:79], v[150:153], v[206:209], v[76:79]
	v_mfma_f32_16x16x32_bf16 v[72:75], v[158:161], v[206:209], v[72:75]
	v_mfma_f32_16x16x32_bf16 v[116:119], v[162:165], v[178:181], 0
	v_mfma_f32_16x16x32_bf16 v[112:115], v[170:173], v[178:181], 0
	v_mfma_f32_16x16x32_bf16 v[100:103], v[162:165], v[186:189], 0
	v_mfma_f32_16x16x32_bf16 v[96:99], v[170:173], v[186:189], 0
	v_mfma_f32_16x16x32_bf16 v[84:87], v[162:165], v[194:197], 0
	v_mfma_f32_16x16x32_bf16 v[80:83], v[170:173], v[194:197], 0
	v_mfma_f32_16x16x32_bf16 v[68:71], v[162:165], v[202:205], 0
	v_mfma_f32_16x16x32_bf16 v[64:67], v[170:173], v[202:205], 0
	v_mfma_f32_16x16x32_bf16 v[116:119], v[166:169], v[182:185], v[116:119]
	v_mfma_f32_16x16x32_bf16 v[112:115], v[174:177], v[182:185], v[112:115]
	v_mfma_f32_16x16x32_bf16 v[100:103], v[166:169], v[190:193], v[100:103]
	v_mfma_f32_16x16x32_bf16 v[96:99], v[174:177], v[190:193], v[96:99]
	v_mfma_f32_16x16x32_bf16 v[84:87], v[166:169], v[198:201], v[84:87]
	v_mfma_f32_16x16x32_bf16 v[80:83], v[174:177], v[198:201], v[80:83]
	v_mfma_f32_16x16x32_bf16 v[68:71], v[166:169], v[206:209], v[68:71]
	v_mfma_f32_16x16x32_bf16 v[64:67], v[174:177], v[206:209], v[64:67]
	s_barrier
	s_add_i32 s14, s30, s22
	v_lshl_add_u64 v[210:211], s[18:19], 0, v[130:131]
	s_mov_b32 m0, s14
	ds_read_b128 v[178:181], v149 offset:16384
	ds_read_b128 v[182:185], v149 offset:17408
	ds_read_b128 v[186:189], v149 offset:18432
	ds_read_b128 v[190:193], v149 offset:19456
	ds_read_b128 v[194:197], v149 offset:20480
	ds_read_b128 v[198:201], v149 offset:21504
	ds_read_b128 v[202:205], v149 offset:22528
	ds_read_b128 v[206:209], v149 offset:23552
	global_load_lds_dwordx4 v[210:211], off
	s_add_i32 m0, s14, 0x2000
	s_add_u32 s14, s18, 0xb0000
	v_lshl_add_u64 v[212:213], s[18:19], 0, v[128:129]
	s_addc_u32 s15, s19, 0
	s_add_i32 s40, s31, s22
	global_load_lds_dwordx4 v[212:213], off
	v_lshl_add_u64 v[214:215], s[14:15], 0, v[130:131]
	s_mov_b32 m0, s40
	v_lshl_add_u64 v[216:217], s[20:21], 0, v[128:129]
	global_load_lds_dwordx4 v[214:215], off
	v_lshl_add_u64 v[214:215], s[14:15], 0, v[128:129]
	s_add_i32 m0, s40, 0x2000
	s_nop 0
	global_load_lds_dwordx4 v[214:215], off
	v_lshl_add_u64 v[214:215], s[20:21], 0, v[130:131]
	s_mov_b32 m0, s23
	s_nop 0
	global_load_lds_dwordx4 v[214:215], off
	s_mov_b32 m0, s24
	s_nop 0
	global_load_lds_dwordx4 v[216:217], off
	s_waitcnt vmcnt(8)
	s_waitcnt lgkmcnt(0)
	s_barrier
	s_waitcnt lgkmcnt(0)
	v_mfma_f32_16x16x32_bf16 v[60:63], v[142:145], v[178:181], 0
	v_mfma_f32_16x16x32_bf16 v[56:59], v[154:157], v[178:181], 0
	v_mfma_f32_16x16x32_bf16 v[44:47], v[142:145], v[186:189], 0
	v_mfma_f32_16x16x32_bf16 v[40:43], v[154:157], v[186:189], 0
	v_mfma_f32_16x16x32_bf16 v[28:31], v[142:145], v[194:197], 0
	v_mfma_f32_16x16x32_bf16 v[24:27], v[154:157], v[194:197], 0
	v_mfma_f32_16x16x32_bf16 v[12:15], v[142:145], v[202:205], 0
	v_mfma_f32_16x16x32_bf16 v[8:11], v[154:157], v[202:205], 0
	v_mfma_f32_16x16x32_bf16 v[60:63], v[150:153], v[182:185], v[60:63]
	v_mfma_f32_16x16x32_bf16 v[56:59], v[158:161], v[182:185], v[56:59]
	v_mfma_f32_16x16x32_bf16 v[44:47], v[150:153], v[190:193], v[44:47]
	v_mfma_f32_16x16x32_bf16 v[40:43], v[158:161], v[190:193], v[40:43]
	v_mfma_f32_16x16x32_bf16 v[28:31], v[150:153], v[198:201], v[28:31]
	v_mfma_f32_16x16x32_bf16 v[24:27], v[158:161], v[198:201], v[24:27]
	v_mfma_f32_16x16x32_bf16 v[12:15], v[150:153], v[206:209], v[12:15]
	v_mfma_f32_16x16x32_bf16 v[8:11], v[158:161], v[206:209], v[8:11]
	v_mfma_f32_16x16x32_bf16 v[52:55], v[162:165], v[178:181], 0
	v_mfma_f32_16x16x32_bf16 v[48:51], v[170:173], v[178:181], 0
	v_mfma_f32_16x16x32_bf16 v[36:39], v[162:165], v[186:189], 0
	v_mfma_f32_16x16x32_bf16 v[32:35], v[170:173], v[186:189], 0
	v_mfma_f32_16x16x32_bf16 v[20:23], v[162:165], v[194:197], 0
	v_mfma_f32_16x16x32_bf16 v[16:19], v[170:173], v[194:197], 0
	v_mfma_f32_16x16x32_bf16 v[4:7], v[162:165], v[202:205], 0
	v_mfma_f32_16x16x32_bf16 v[0:3], v[170:173], v[202:205], 0
	v_mfma_f32_16x16x32_bf16 v[52:55], v[166:169], v[182:185], v[52:55]
	v_mfma_f32_16x16x32_bf16 v[48:51], v[174:177], v[182:185], v[48:51]
	v_mfma_f32_16x16x32_bf16 v[36:39], v[166:169], v[190:193], v[36:39]
	v_mfma_f32_16x16x32_bf16 v[32:35], v[174:177], v[190:193], v[32:35]
	v_mfma_f32_16x16x32_bf16 v[20:23], v[166:169], v[198:201], v[20:23]
	v_mfma_f32_16x16x32_bf16 v[16:19], v[174:177], v[198:201], v[16:19]
	v_mfma_f32_16x16x32_bf16 v[4:7], v[166:169], v[206:209], v[4:7]
	v_mfma_f32_16x16x32_bf16 v[0:3], v[174:177], v[206:209], v[0:3]
	s_barrier
	s_add_i32 s40, 0, 0x18000
	s_add_i32 s41, 0, 0x1c000
	v_add_u32_e32 v158, s40, v146
	v_add_u32_e32 v174, s41, v146
	ds_read_b128 v[142:145], v158
	ds_read_b128 v[150:153], v158 offset:1024
	ds_read_b128 v[154:157], v158 offset:2048
	ds_read_b128 v[158:161], v158 offset:3072
	ds_read_b128 v[162:165], v174
	ds_read_b128 v[166:169], v174 offset:1024
	ds_read_b128 v[170:173], v174 offset:2048
	ds_read_b128 v[174:177], v174 offset:3072
	s_add_u32 s14, s20, 0xb0000
	s_addc_u32 s15, s21, 0
	s_mov_b32 m0, s25
	v_lshl_add_u64 v[218:219], s[14:15], 0, v[130:131]
	ds_read_b128 v[178:181], v149 offset:32768
	ds_read_b128 v[182:185], v149 offset:33792
	ds_read_b128 v[186:189], v149 offset:34816
	ds_read_b128 v[190:193], v149 offset:35840
	ds_read_b128 v[194:197], v149 offset:36864
	ds_read_b128 v[198:201], v149 offset:37888
	ds_read_b128 v[202:205], v149 offset:38912
	ds_read_b128 v[206:209], v149 offset:39936
	global_load_lds_dwordx4 v[218:219], off
	v_lshl_add_u64 v[218:219], s[14:15], 0, v[128:129]
	s_mov_b32 m0, s26
	s_nop 0
	global_load_lds_dwordx4 v[218:219], off
	s_waitcnt vmcnt(8)
	s_waitcnt lgkmcnt(0)
	s_barrier
	s_waitcnt lgkmcnt(0)
	v_mfma_f32_16x16x32_bf16 v[124:127], v[142:145], v[178:181], v[124:127]
	v_mfma_f32_16x16x32_bf16 v[120:123], v[154:157], v[178:181], v[120:123]
	v_mfma_f32_16x16x32_bf16 v[108:111], v[142:145], v[186:189], v[108:111]
	v_mfma_f32_16x16x32_bf16 v[104:107], v[154:157], v[186:189], v[104:107]
	v_mfma_f32_16x16x32_bf16 v[92:95], v[142:145], v[194:197], v[92:95]
	v_mfma_f32_16x16x32_bf16 v[88:91], v[154:157], v[194:197], v[88:91]
	v_mfma_f32_16x16x32_bf16 v[76:79], v[142:145], v[202:205], v[76:79]
	v_mfma_f32_16x16x32_bf16 v[72:75], v[154:157], v[202:205], v[72:75]
	v_mfma_f32_16x16x32_bf16 v[124:127], v[150:153], v[182:185], v[124:127]
	v_mfma_f32_16x16x32_bf16 v[120:123], v[158:161], v[182:185], v[120:123]
	v_mfma_f32_16x16x32_bf16 v[108:111], v[150:153], v[190:193], v[108:111]
	v_mfma_f32_16x16x32_bf16 v[104:107], v[158:161], v[190:193], v[104:107]
	v_mfma_f32_16x16x32_bf16 v[92:95], v[150:153], v[198:201], v[92:95]
	v_mfma_f32_16x16x32_bf16 v[88:91], v[158:161], v[198:201], v[88:91]
	v_mfma_f32_16x16x32_bf16 v[76:79], v[150:153], v[206:209], v[76:79]
	v_mfma_f32_16x16x32_bf16 v[72:75], v[158:161], v[206:209], v[72:75]
	v_mfma_f32_16x16x32_bf16 v[116:119], v[162:165], v[178:181], v[116:119]
	v_mfma_f32_16x16x32_bf16 v[112:115], v[170:173], v[178:181], v[112:115]
	v_mfma_f32_16x16x32_bf16 v[100:103], v[162:165], v[186:189], v[100:103]
	v_mfma_f32_16x16x32_bf16 v[96:99], v[170:173], v[186:189], v[96:99]
	v_mfma_f32_16x16x32_bf16 v[84:87], v[162:165], v[194:197], v[84:87]
	v_mfma_f32_16x16x32_bf16 v[80:83], v[170:173], v[194:197], v[80:83]
	v_mfma_f32_16x16x32_bf16 v[68:71], v[162:165], v[202:205], v[68:71]
	v_mfma_f32_16x16x32_bf16 v[64:67], v[170:173], v[202:205], v[64:67]
	v_mfma_f32_16x16x32_bf16 v[116:119], v[166:169], v[182:185], v[116:119]
	v_mfma_f32_16x16x32_bf16 v[112:115], v[174:177], v[182:185], v[112:115]
	v_mfma_f32_16x16x32_bf16 v[100:103], v[166:169], v[190:193], v[100:103]
	v_mfma_f32_16x16x32_bf16 v[96:99], v[174:177], v[190:193], v[96:99]
	v_mfma_f32_16x16x32_bf16 v[84:87], v[166:169], v[198:201], v[84:87]
	v_mfma_f32_16x16x32_bf16 v[80:83], v[174:177], v[198:201], v[80:83]
	v_mfma_f32_16x16x32_bf16 v[68:71], v[166:169], v[206:209], v[68:71]
	v_mfma_f32_16x16x32_bf16 v[64:67], v[174:177], v[206:209], v[64:67]
	s_barrier
	s_add_i32 s14, s40, s22
	v_lshl_add_u64 v[210:211], v[210:211], 0, s[8:9]
	s_mov_b32 m0, s14
	ds_read_b128 v[178:181], v149 offset:49152
	ds_read_b128 v[182:185], v149 offset:50176
	ds_read_b128 v[186:189], v149 offset:51200
	ds_read_b128 v[190:193], v149 offset:52224
	ds_read_b128 v[194:197], v149 offset:53248
	ds_read_b128 v[198:201], v149 offset:54272
	ds_read_b128 v[202:205], v149 offset:55296
	ds_read_b128 v[206:209], v149 offset:56320
	global_load_lds_dwordx4 v[210:211], off
	s_add_i32 m0, s14, 0x2000
	s_add_u32 s14, s18, 0xb0080
	v_lshl_add_u64 v[210:211], v[212:213], 0, s[8:9]
	s_addc_u32 s15, s19, 0
	s_add_i32 s18, s41, s22
	global_load_lds_dwordx4 v[210:211], off
	v_lshl_add_u64 v[210:211], s[14:15], 0, v[130:131]
	s_mov_b32 m0, s18
	s_nop 0
	global_load_lds_dwordx4 v[210:211], off
	v_lshl_add_u64 v[210:211], s[14:15], 0, v[128:129]
	s_add_i32 m0, s18, 0x2000
	s_nop 0
	global_load_lds_dwordx4 v[210:211], off
	v_lshl_add_u64 v[210:211], v[214:215], 0, s[8:9]
	s_mov_b32 m0, s27
	s_nop 0
	global_load_lds_dwordx4 v[210:211], off
	v_lshl_add_u64 v[210:211], v[216:217], 0, s[8:9]
	s_mov_b32 m0, s28
	s_nop 0
	global_load_lds_dwordx4 v[210:211], off
	s_waitcnt vmcnt(8)
	s_waitcnt lgkmcnt(0)
	s_barrier
	s_waitcnt lgkmcnt(0)
	v_mfma_f32_16x16x32_bf16 v[60:63], v[142:145], v[178:181], v[60:63]
	v_mfma_f32_16x16x32_bf16 v[56:59], v[154:157], v[178:181], v[56:59]
	v_mfma_f32_16x16x32_bf16 v[44:47], v[142:145], v[186:189], v[44:47]
	v_mfma_f32_16x16x32_bf16 v[40:43], v[154:157], v[186:189], v[40:43]
	v_mfma_f32_16x16x32_bf16 v[28:31], v[142:145], v[194:197], v[28:31]
	v_mfma_f32_16x16x32_bf16 v[24:27], v[154:157], v[194:197], v[24:27]
	v_mfma_f32_16x16x32_bf16 v[12:15], v[142:145], v[202:205], v[12:15]
	v_mfma_f32_16x16x32_bf16 v[8:11], v[154:157], v[202:205], v[8:11]
	v_mfma_f32_16x16x32_bf16 v[60:63], v[150:153], v[182:185], v[60:63]
	v_mfma_f32_16x16x32_bf16 v[56:59], v[158:161], v[182:185], v[56:59]
	v_mfma_f32_16x16x32_bf16 v[44:47], v[150:153], v[190:193], v[44:47]
	v_mfma_f32_16x16x32_bf16 v[40:43], v[158:161], v[190:193], v[40:43]
	v_mfma_f32_16x16x32_bf16 v[28:31], v[150:153], v[198:201], v[28:31]
	v_mfma_f32_16x16x32_bf16 v[24:27], v[158:161], v[198:201], v[24:27]
	v_mfma_f32_16x16x32_bf16 v[12:15], v[150:153], v[206:209], v[12:15]
	v_mfma_f32_16x16x32_bf16 v[8:11], v[158:161], v[206:209], v[8:11]
	v_mfma_f32_16x16x32_bf16 v[52:55], v[162:165], v[178:181], v[52:55]
	v_mfma_f32_16x16x32_bf16 v[48:51], v[170:173], v[178:181], v[48:51]
	v_mfma_f32_16x16x32_bf16 v[36:39], v[162:165], v[186:189], v[36:39]
	v_mfma_f32_16x16x32_bf16 v[32:35], v[170:173], v[186:189], v[32:35]
	v_mfma_f32_16x16x32_bf16 v[20:23], v[162:165], v[194:197], v[20:23]
	v_mfma_f32_16x16x32_bf16 v[16:19], v[170:173], v[194:197], v[16:19]
	v_mfma_f32_16x16x32_bf16 v[4:7], v[162:165], v[202:205], v[4:7]
	v_mfma_f32_16x16x32_bf16 v[0:3], v[170:173], v[202:205], v[0:3]
	v_mfma_f32_16x16x32_bf16 v[52:55], v[166:169], v[182:185], v[52:55]
	v_mfma_f32_16x16x32_bf16 v[48:51], v[174:177], v[182:185], v[48:51]
	v_mfma_f32_16x16x32_bf16 v[36:39], v[166:169], v[190:193], v[36:39]
	v_mfma_f32_16x16x32_bf16 v[32:35], v[174:177], v[190:193], v[32:35]
	v_mfma_f32_16x16x32_bf16 v[20:23], v[166:169], v[198:201], v[20:23]
	v_mfma_f32_16x16x32_bf16 v[16:19], v[174:177], v[198:201], v[16:19]
	v_mfma_f32_16x16x32_bf16 v[4:7], v[166:169], v[206:209], v[4:7]
	v_mfma_f32_16x16x32_bf16 v[0:3], v[174:177], v[206:209], v[0:3]
	s_barrier
	s_add_i32 s39, s39, 2
	s_add_u32 s37, s37, 0x100
	s_addc_u32 s38, s38, 0
	s_cmp_gt_u32 s39, 41
	s_mov_b64 s[14:15], s[16:17]
	s_cbranch_scc1 .Lpeel_x5
